# conv-tail schedule C: W1,W2 of layer 0 in the prologue; lighter tails, lora tail takes W1 of layer 1
# baseline (speedup 1.0000x reference)
.LBB0_76:
	s_mov_b32 s98, 0
	s_mov_b32 s17, 0x3
	s_cmp_eq_u32 s88, 0
	s_cbranch_scc1 .LBB0_81
	s_mov_b32 s17, 0
	s_mov_b32 s99, 0
	s_cmp_eq_u32 s88, 1
	s_cselect_b32 s17, 0x4, s17
	s_cselect_b32 s99, 0x96, s99
	s_cmp_eq_u32 s88, 3
	s_cselect_b32 s17, 0x90, s17
	s_cselect_b32 s99, 0x8e, s99
	s_cmp_eq_u32 s88, 5
	s_cselect_b32 s17, 0x40, s17
	s_cselect_b32 s99, 0xc, s99
	s_cmp_eq_u32 s88, 7
	s_cselect_b32 s17, 0x28, s17
	s_cselect_b32 s99, 0xd3, s99
	s_cmp_eq_u32 s88, 10
	s_cselect_b32 s17, 0x100, s17
	s_cselect_b32 s99, 0x96, s99
	s_cmp_eq_u32 s88, 12
	s_cselect_b32 s17, 0x600, s17
	s_cselect_b32 s99, 0x96, s99
	s_cmp_eq_u32 s88, 14
	s_cselect_b32 s17, 0x800, s17
	s_cselect_b32 s99, 0x8e, s99
	s_cmp_eq_u32 s17, 0
	s_cbranch_scc1 .LBB0_78
	s_cmp_lt_u32 s2, s99
	s_cbranch_scc0 .Lcv_idle

.LBB0_606:
	s_and_b64 vcc, exec, s[0:1]
	s_cbranch_vccz .LBB0_508
	s_waitcnt vmcnt(0)
	v_lshrrev_b32_e32 v90, 4, v241
	v_bfe_u32 v91, v241, 3, 1
	v_and_b32_e32 v86, 15, v241
	v_lshlrev_b32_e32 v90, 1, v90
	v_lshlrev_b32_e32 v86, 4, v86
	v_add_u32_e32 v92, v90, v91
	v_xor_b32_e32 v91, 1, v91
	v_add_u32_e32 v93, v90, v91
	s_lshl_b32 s0, s10, 5
	v_lshlrev_b32_e32 v89, 2, v92
	v_add_u32_e32 v92, s0, v92
	v_add_u32_e32 v93, s0, v93
	v_add_u32_e32 v89, 0x18000, v89
	v_lshlrev_b32_e32 v87, 2, v92
	v_lshlrev_b32_e32 v88, 2, v93
	v_mov_b32_e32 v0, 0
	v_mov_b32_e32 v1, 0
	v_mov_b32_e32 v2, 0
	v_mov_b32_e32 v3, 0
	v_mov_b32_e32 v4, 0
	v_mov_b32_e32 v5, 0
	v_mov_b32_e32 v6, 0
	v_mov_b32_e32 v7, 0
	s_waitcnt lgkmcnt(0)
	s_barrier
	s_mov_b32 s4, 0
	s_nop 0
	s_nop 0
	s_nop 0
	s_nop 0
	s_nop 0
	s_nop 0
	s_nop 0
	s_nop 0
	s_nop 0
	s_nop 0
	s_nop 0
	s_nop 0
	s_nop 0
.Lrec_chunk:
	s_and_b32 s0, s4, 1
	s_mul_i32 s1, s0, 0xc000
	s_lshl_b32 s5, s0, 8
	v_add_u32_e32 v80, s1, v86
	v_add_u32_e32 v81, s1, v87
	v_add_u32_e32 v82, s1, v88
	s_add_i32 s5, s5, 0x1a100
	s_lshl_b32 s0, s0, 12
	v_mov_b32_e32 v83, s5
	v_add_u32_e32 v84, s0, v89
	ds_read_b128 v[12:15], v80 offset:768
	ds_read_b128 v[16:19], v80 offset:0
	ds_read_b128 v[20:23], v80 offset:256
	ds_read_b128 v[24:27], v80 offset:512
	ds_read_b128 v[28:31], v80 offset:1024
	ds_read_b32 v32, v81 offset:1280
	ds_read_b32 v33, v82 offset:1280
	s_waitcnt lgkmcnt(5)
	v_pk_mul_f32 v[8:9], v[0:1], v[12:13] op_sel_hi:[1,0]
	v_pk_mul_f32 v[10:11], v[0:1], v[16:17] op_sel_hi:[1,0]
	ds_read_b128 v[40:43], v80 offset:2304
	v_pk_fma_f32 v[8:9], v[2:3], v[12:13], v[8:9] op_sel:[0,1,0]
	v_pk_fma_f32 v[10:11], v[2:3], v[16:17], v[10:11] op_sel:[0,1,0]
	ds_read_b128 v[44:47], v80 offset:1536
	v_pk_fma_f32 v[8:9], v[4:5], v[14:15], v[8:9] op_sel_hi:[1,0,1]
	v_pk_fma_f32 v[10:11], v[4:5], v[18:19], v[10:11] op_sel_hi:[1,0,1]
	ds_read_b128 v[48:51], v80 offset:1792
	v_pk_fma_f32 v[8:9], v[6:7], v[14:15], v[8:9] op_sel:[0,1,0]
	v_pk_fma_f32 v[10:11], v[6:7], v[18:19], v[10:11] op_sel:[0,1,0]
	ds_read_b128 v[52:55], v80 offset:2048
	v_add_f32_dpp v74, v9, v8 row_ror:8 row_mask:0xf bank_mask:0xf bound_ctrl:1
	v_add_f32_dpp v75, v11, v10 row_ror:8 row_mask:0xf bank_mask:0xf bound_ctrl:1
	ds_read_b128 v[56:59], v80 offset:2560
	v_add_f32_dpp v74, v74, v74 quad_perm:[1,0,3,2] row_mask:0xf bank_mask:0xf bound_ctrl:1
	v_add_f32_dpp v75, v75, v75 quad_perm:[1,0,3,2] row_mask:0xf bank_mask:0xf bound_ctrl:1
	ds_read_b32 v60, v81 offset:2816
	v_add_f32_dpp v74, v74, v74 quad_perm:[2,3,0,1] row_mask:0xf bank_mask:0xf bound_ctrl:1
	v_add_f32_dpp v75, v75, v75 quad_perm:[2,3,0,1] row_mask:0xf bank_mask:0xf bound_ctrl:1
	ds_read_b32 v61, v82 offset:2816
	v_add_f32_dpp v76, v74, v74 row_half_mirror row_mask:0xf bank_mask:0xf bound_ctrl:1
	v_add_f32_dpp v36, v75, v75 row_half_mirror row_mask:0xf bank_mask:0xf bound_ctrl:1
	s_nop 0
	v_mov_b32_dpp v77, v76 row_ror:8 row_mask:0xf bank_mask:0xf bound_ctrl:1
	s_waitcnt lgkmcnt(7)
	v_pk_mul_f32 v[66:67], v[76:77], v[28:29] op_sel_hi:[1,0]
	v_pk_mul_f32 v[68:69], v[76:77], v[28:29] op_sel:[0,1]
	v_pk_mul_f32 v[70:71], v[76:77], v[30:31] op_sel_hi:[1,0]
	v_pk_mul_f32 v[72:73], v[76:77], v[30:31] op_sel:[0,1]
	v_pk_fma_f32 v[66:67], v[32:33], v[24:25], v[66:67] op_sel_hi:[1,0,1]
	v_pk_fma_f32 v[68:69], v[32:33], v[24:25], v[68:69] op_sel:[0,1,0]
	v_pk_fma_f32 v[70:71], v[32:33], v[26:27], v[70:71] op_sel_hi:[1,0,1]
	v_pk_fma_f32 v[72:73], v[32:33], v[26:27], v[72:73] op_sel:[0,1,0]
	v_pk_fma_f32 v[0:1], v[0:1], v[20:21], v[66:67] op_sel_hi:[1,0,1]
	v_pk_fma_f32 v[2:3], v[2:3], v[20:21], v[68:69] op_sel:[0,1,0]
	v_pk_fma_f32 v[4:5], v[4:5], v[22:23], v[70:71] op_sel_hi:[1,0,1]
	v_pk_fma_f32 v[6:7], v[6:7], v[22:23], v[72:73] op_sel:[0,1,0]
	ds_write_b32 v84, v36 offset:0
	ds_write_b32 v84, v76 offset:12288
	s_waitcnt lgkmcnt(7)
	v_pk_mul_f32 v[8:9], v[0:1], v[40:41] op_sel_hi:[1,0]
	v_pk_mul_f32 v[10:11], v[0:1], v[44:45] op_sel_hi:[1,0]
	ds_read_b128 v[12:15], v80 offset:3840
	v_pk_fma_f32 v[8:9], v[2:3], v[40:41], v[8:9] op_sel:[0,1,0]
	v_pk_fma_f32 v[10:11], v[2:3], v[44:45], v[10:11] op_sel:[0,1,0]
	ds_read_b128 v[16:19], v80 offset:3072
	v_pk_fma_f32 v[8:9], v[4:5], v[42:43], v[8:9] op_sel_hi:[1,0,1]
	v_pk_fma_f32 v[10:11], v[4:5], v[46:47], v[10:11] op_sel_hi:[1,0,1]
	ds_read_b128 v[20:23], v80 offset:3328
	v_pk_fma_f32 v[8:9], v[6:7], v[42:43], v[8:9] op_sel:[0,1,0]
	v_pk_fma_f32 v[10:11], v[6:7], v[46:47], v[10:11] op_sel:[0,1,0]
	ds_read_b128 v[24:27], v80 offset:3584
	v_add_f32_dpp v74, v9, v8 row_ror:8 row_mask:0xf bank_mask:0xf bound_ctrl:1
	v_add_f32_dpp v75, v11, v10 row_ror:8 row_mask:0xf bank_mask:0xf bound_ctrl:1
	ds_read_b128 v[28:31], v80 offset:4096
	v_add_f32_dpp v74, v74, v74 quad_perm:[1,0,3,2] row_mask:0xf bank_mask:0xf bound_ctrl:1
	v_add_f32_dpp v75, v75, v75 quad_perm:[1,0,3,2] row_mask:0xf bank_mask:0xf bound_ctrl:1
	ds_read_b32 v32, v81 offset:4352
	v_add_f32_dpp v74, v74, v74 quad_perm:[2,3,0,1] row_mask:0xf bank_mask:0xf bound_ctrl:1
	v_add_f32_dpp v75, v75, v75 quad_perm:[2,3,0,1] row_mask:0xf bank_mask:0xf bound_ctrl:1
	ds_read_b32 v33, v82 offset:4352
	v_add_f32_dpp v76, v74, v74 row_half_mirror row_mask:0xf bank_mask:0xf bound_ctrl:1
	v_add_f32_dpp v64, v75, v75 row_half_mirror row_mask:0xf bank_mask:0xf bound_ctrl:1
	s_nop 0
	v_mov_b32_dpp v77, v76 row_ror:8 row_mask:0xf bank_mask:0xf bound_ctrl:1
	s_waitcnt lgkmcnt(9)
	v_pk_mul_f32 v[66:67], v[76:77], v[56:57] op_sel_hi:[1,0]
	v_pk_mul_f32 v[68:69], v[76:77], v[56:57] op_sel:[0,1]
	v_pk_mul_f32 v[70:71], v[76:77], v[58:59] op_sel_hi:[1,0]
	v_pk_mul_f32 v[72:73], v[76:77], v[58:59] op_sel:[0,1]
	v_pk_fma_f32 v[66:67], v[60:61], v[52:53], v[66:67] op_sel_hi:[1,0,1]
	v_pk_fma_f32 v[68:69], v[60:61], v[52:53], v[68:69] op_sel:[0,1,0]
	v_pk_fma_f32 v[70:71], v[60:61], v[54:55], v[70:71] op_sel_hi:[1,0,1]
	v_pk_fma_f32 v[72:73], v[60:61], v[54:55], v[72:73] op_sel:[0,1,0]
	v_pk_fma_f32 v[0:1], v[0:1], v[48:49], v[66:67] op_sel_hi:[1,0,1]
	v_pk_fma_f32 v[2:3], v[2:3], v[48:49], v[68:69] op_sel:[0,1,0]
	v_pk_fma_f32 v[4:5], v[4:5], v[50:51], v[70:71] op_sel_hi:[1,0,1]
	v_pk_fma_f32 v[6:7], v[6:7], v[50:51], v[72:73] op_sel:[0,1,0]
	ds_write_b32 v84, v64 offset:128
	ds_write_b32 v84, v76 offset:12416
	s_waitcnt lgkmcnt(7)
	v_pk_mul_f32 v[8:9], v[0:1], v[12:13] op_sel_hi:[1,0]
	v_pk_mul_f32 v[10:11], v[0:1], v[16:17] op_sel_hi:[1,0]
	ds_read_b128 v[40:43], v80 offset:5376
	v_pk_fma_f32 v[8:9], v[2:3], v[12:13], v[8:9] op_sel:[0,1,0]
	v_pk_fma_f32 v[10:11], v[2:3], v[16:17], v[10:11] op_sel:[0,1,0]
	ds_read_b128 v[44:47], v80 offset:4608
	v_pk_fma_f32 v[8:9], v[4:5], v[14:15], v[8:9] op_sel_hi:[1,0,1]
	v_pk_fma_f32 v[10:11], v[4:5], v[18:19], v[10:11] op_sel_hi:[1,0,1]
	ds_read_b128 v[48:51], v80 offset:4864
	v_pk_fma_f32 v[8:9], v[6:7], v[14:15], v[8:9] op_sel:[0,1,0]
	v_pk_fma_f32 v[10:11], v[6:7], v[18:19], v[10:11] op_sel:[0,1,0]
	ds_read_b128 v[52:55], v80 offset:5120
	v_add_f32_dpp v74, v9, v8 row_ror:8 row_mask:0xf bank_mask:0xf bound_ctrl:1
	v_add_f32_dpp v75, v11, v10 row_ror:8 row_mask:0xf bank_mask:0xf bound_ctrl:1
	ds_read_b128 v[56:59], v80 offset:5632
	v_add_f32_dpp v74, v74, v74 quad_perm:[1,0,3,2] row_mask:0xf bank_mask:0xf bound_ctrl:1
	v_add_f32_dpp v75, v75, v75 quad_perm:[1,0,3,2] row_mask:0xf bank_mask:0xf bound_ctrl:1
	ds_read_b32 v60, v81 offset:5888
	v_add_f32_dpp v74, v74, v74 quad_perm:[2,3,0,1] row_mask:0xf bank_mask:0xf bound_ctrl:1
	v_add_f32_dpp v75, v75, v75 quad_perm:[2,3,0,1] row_mask:0xf bank_mask:0xf bound_ctrl:1
	ds_read_b32 v61, v82 offset:5888
	v_add_f32_dpp v76, v74, v74 row_half_mirror row_mask:0xf bank_mask:0xf bound_ctrl:1
	v_add_f32_dpp v36, v75, v75 row_half_mirror row_mask:0xf bank_mask:0xf bound_ctrl:1
	s_nop 0
	v_mov_b32_dpp v77, v76 row_ror:8 row_mask:0xf bank_mask:0xf bound_ctrl:1
	s_waitcnt lgkmcnt(9)
	v_pk_mul_f32 v[66:67], v[76:77], v[28:29] op_sel_hi:[1,0]
	v_pk_mul_f32 v[68:69], v[76:77], v[28:29] op_sel:[0,1]
	v_pk_mul_f32 v[70:71], v[76:77], v[30:31] op_sel_hi:[1,0]
	v_pk_mul_f32 v[72:73], v[76:77], v[30:31] op_sel:[0,1]
	v_pk_fma_f32 v[66:67], v[32:33], v[24:25], v[66:67] op_sel_hi:[1,0,1]
	v_pk_fma_f32 v[68:69], v[32:33], v[24:25], v[68:69] op_sel:[0,1,0]
	v_pk_fma_f32 v[70:71], v[32:33], v[26:27], v[70:71] op_sel_hi:[1,0,1]
	v_pk_fma_f32 v[72:73], v[32:33], v[26:27], v[72:73] op_sel:[0,1,0]
	v_pk_fma_f32 v[0:1], v[0:1], v[20:21], v[66:67] op_sel_hi:[1,0,1]
	v_pk_fma_f32 v[2:3], v[2:3], v[20:21], v[68:69] op_sel:[0,1,0]
	v_pk_fma_f32 v[4:5], v[4:5], v[22:23], v[70:71] op_sel_hi:[1,0,1]
	v_pk_fma_f32 v[6:7], v[6:7], v[22:23], v[72:73] op_sel:[0,1,0]
	ds_write_b32 v84, v36 offset:256
	ds_write_b32 v84, v76 offset:12544
	s_waitcnt lgkmcnt(7)
	v_pk_mul_f32 v[8:9], v[0:1], v[40:41] op_sel_hi:[1,0]
	v_pk_mul_f32 v[10:11], v[0:1], v[44:45] op_sel_hi:[1,0]
	ds_read_b128 v[12:15], v80 offset:6912
	v_pk_fma_f32 v[8:9], v[2:3], v[40:41], v[8:9] op_sel:[0,1,0]
	v_pk_fma_f32 v[10:11], v[2:3], v[44:45], v[10:11] op_sel:[0,1,0]
	ds_read_b128 v[16:19], v80 offset:6144
	v_pk_fma_f32 v[8:9], v[4:5], v[42:43], v[8:9] op_sel_hi:[1,0,1]
	v_pk_fma_f32 v[10:11], v[4:5], v[46:47], v[10:11] op_sel_hi:[1,0,1]
	ds_read_b128 v[20:23], v80 offset:6400
	v_pk_fma_f32 v[8:9], v[6:7], v[42:43], v[8:9] op_sel:[0,1,0]
	v_pk_fma_f32 v[10:11], v[6:7], v[46:47], v[10:11] op_sel:[0,1,0]
	ds_read_b128 v[24:27], v80 offset:6656
	v_add_f32_dpp v74, v9, v8 row_ror:8 row_mask:0xf bank_mask:0xf bound_ctrl:1
	v_add_f32_dpp v75, v11, v10 row_ror:8 row_mask:0xf bank_mask:0xf bound_ctrl:1
	ds_read_b128 v[28:31], v80 offset:7168
	v_add_f32_dpp v74, v74, v74 quad_perm:[1,0,3,2] row_mask:0xf bank_mask:0xf bound_ctrl:1
	v_add_f32_dpp v75, v75, v75 quad_perm:[1,0,3,2] row_mask:0xf bank_mask:0xf bound_ctrl:1
	ds_read_b32 v32, v81 offset:7424
	v_add_f32_dpp v74, v74, v74 quad_perm:[2,3,0,1] row_mask:0xf bank_mask:0xf bound_ctrl:1
	v_add_f32_dpp v75, v75, v75 quad_perm:[2,3,0,1] row_mask:0xf bank_mask:0xf bound_ctrl:1
	ds_read_b32 v33, v82 offset:7424
	v_add_f32_dpp v76, v74, v74 row_half_mirror row_mask:0xf bank_mask:0xf bound_ctrl:1
	v_add_f32_dpp v64, v75, v75 row_half_mirror row_mask:0xf bank_mask:0xf bound_ctrl:1
	s_nop 0
	v_mov_b32_dpp v77, v76 row_ror:8 row_mask:0xf bank_mask:0xf bound_ctrl:1
	s_waitcnt lgkmcnt(9)
	v_pk_mul_f32 v[66:67], v[76:77], v[56:57] op_sel_hi:[1,0]
	v_pk_mul_f32 v[68:69], v[76:77], v[56:57] op_sel:[0,1]
	v_pk_mul_f32 v[70:71], v[76:77], v[58:59] op_sel_hi:[1,0]
	v_pk_mul_f32 v[72:73], v[76:77], v[58:59] op_sel:[0,1]
	v_pk_fma_f32 v[66:67], v[60:61], v[52:53], v[66:67] op_sel_hi:[1,0,1]
	v_pk_fma_f32 v[68:69], v[60:61], v[52:53], v[68:69] op_sel:[0,1,0]
	v_pk_fma_f32 v[70:71], v[60:61], v[54:55], v[70:71] op_sel_hi:[1,0,1]
	v_pk_fma_f32 v[72:73], v[60:61], v[54:55], v[72:73] op_sel:[0,1,0]
	v_pk_fma_f32 v[0:1], v[0:1], v[48:49], v[66:67] op_sel_hi:[1,0,1]
	v_pk_fma_f32 v[2:3], v[2:3], v[48:49], v[68:69] op_sel:[0,1,0]
	v_pk_fma_f32 v[4:5], v[4:5], v[50:51], v[70:71] op_sel_hi:[1,0,1]
	v_pk_fma_f32 v[6:7], v[6:7], v[50:51], v[72:73] op_sel:[0,1,0]
	ds_write_b32 v84, v64 offset:384
	ds_write_b32 v84, v76 offset:12672
	s_waitcnt lgkmcnt(7)
	v_pk_mul_f32 v[8:9], v[0:1], v[12:13] op_sel_hi:[1,0]
	v_pk_mul_f32 v[10:11], v[0:1], v[16:17] op_sel_hi:[1,0]
	ds_read_b128 v[40:43], v80 offset:8448
	v_pk_fma_f32 v[8:9], v[2:3], v[12:13], v[8:9] op_sel:[0,1,0]
	v_pk_fma_f32 v[10:11], v[2:3], v[16:17], v[10:11] op_sel:[0,1,0]
	ds_read_b128 v[44:47], v80 offset:7680
	v_pk_fma_f32 v[8:9], v[4:5], v[14:15], v[8:9] op_sel_hi:[1,0,1]
	v_pk_fma_f32 v[10:11], v[4:5], v[18:19], v[10:11] op_sel_hi:[1,0,1]
	ds_read_b128 v[48:51], v80 offset:7936
	v_pk_fma_f32 v[8:9], v[6:7], v[14:15], v[8:9] op_sel:[0,1,0]
	v_pk_fma_f32 v[10:11], v[6:7], v[18:19], v[10:11] op_sel:[0,1,0]
	ds_read_b128 v[52:55], v80 offset:8192
	v_add_f32_dpp v74, v9, v8 row_ror:8 row_mask:0xf bank_mask:0xf bound_ctrl:1
	v_add_f32_dpp v75, v11, v10 row_ror:8 row_mask:0xf bank_mask:0xf bound_ctrl:1
	ds_read_b128 v[56:59], v80 offset:8704
	v_add_f32_dpp v74, v74, v74 quad_perm:[1,0,3,2] row_mask:0xf bank_mask:0xf bound_ctrl:1
	v_add_f32_dpp v75, v75, v75 quad_perm:[1,0,3,2] row_mask:0xf bank_mask:0xf bound_ctrl:1
	ds_read_b32 v60, v81 offset:8960
	v_add_f32_dpp v74, v74, v74 quad_perm:[2,3,0,1] row_mask:0xf bank_mask:0xf bound_ctrl:1
	v_add_f32_dpp v75, v75, v75 quad_perm:[2,3,0,1] row_mask:0xf bank_mask:0xf bound_ctrl:1
	ds_read_b32 v61, v82 offset:8960
	v_add_f32_dpp v76, v74, v74 row_half_mirror row_mask:0xf bank_mask:0xf bound_ctrl:1
	v_add_f32_dpp v36, v75, v75 row_half_mirror row_mask:0xf bank_mask:0xf bound_ctrl:1
	s_nop 0
	v_mov_b32_dpp v77, v76 row_ror:8 row_mask:0xf bank_mask:0xf bound_ctrl:1
	s_waitcnt lgkmcnt(9)
	v_pk_mul_f32 v[66:67], v[76:77], v[28:29] op_sel_hi:[1,0]
	v_pk_mul_f32 v[68:69], v[76:77], v[28:29] op_sel:[0,1]
	v_pk_mul_f32 v[70:71], v[76:77], v[30:31] op_sel_hi:[1,0]
	v_pk_mul_f32 v[72:73], v[76:77], v[30:31] op_sel:[0,1]
	v_pk_fma_f32 v[66:67], v[32:33], v[24:25], v[66:67] op_sel_hi:[1,0,1]
	v_pk_fma_f32 v[68:69], v[32:33], v[24:25], v[68:69] op_sel:[0,1,0]
	v_pk_fma_f32 v[70:71], v[32:33], v[26:27], v[70:71] op_sel_hi:[1,0,1]
	v_pk_fma_f32 v[72:73], v[32:33], v[26:27], v[72:73] op_sel:[0,1,0]
	v_pk_fma_f32 v[0:1], v[0:1], v[20:21], v[66:67] op_sel_hi:[1,0,1]
	v_pk_fma_f32 v[2:3], v[2:3], v[20:21], v[68:69] op_sel:[0,1,0]
	v_pk_fma_f32 v[4:5], v[4:5], v[22:23], v[70:71] op_sel_hi:[1,0,1]
	v_pk_fma_f32 v[6:7], v[6:7], v[22:23], v[72:73] op_sel:[0,1,0]
	ds_write_b32 v84, v36 offset:512
	ds_write_b32 v84, v76 offset:12800
	s_waitcnt lgkmcnt(7)
	v_pk_mul_f32 v[8:9], v[0:1], v[40:41] op_sel_hi:[1,0]
	v_pk_mul_f32 v[10:11], v[0:1], v[44:45] op_sel_hi:[1,0]
	ds_read_b128 v[12:15], v80 offset:9984
	v_pk_fma_f32 v[8:9], v[2:3], v[40:41], v[8:9] op_sel:[0,1,0]
	v_pk_fma_f32 v[10:11], v[2:3], v[44:45], v[10:11] op_sel:[0,1,0]
	ds_read_b128 v[16:19], v80 offset:9216
	v_pk_fma_f32 v[8:9], v[4:5], v[42:43], v[8:9] op_sel_hi:[1,0,1]
	v_pk_fma_f32 v[10:11], v[4:5], v[46:47], v[10:11] op_sel_hi:[1,0,1]
	ds_read_b128 v[20:23], v80 offset:9472
	v_pk_fma_f32 v[8:9], v[6:7], v[42:43], v[8:9] op_sel:[0,1,0]
	v_pk_fma_f32 v[10:11], v[6:7], v[46:47], v[10:11] op_sel:[0,1,0]
	ds_read_b128 v[24:27], v80 offset:9728
	v_add_f32_dpp v74, v9, v8 row_ror:8 row_mask:0xf bank_mask:0xf bound_ctrl:1
	v_add_f32_dpp v75, v11, v10 row_ror:8 row_mask:0xf bank_mask:0xf bound_ctrl:1
	ds_read_b128 v[28:31], v80 offset:10240
	v_add_f32_dpp v74, v74, v74 quad_perm:[1,0,3,2] row_mask:0xf bank_mask:0xf bound_ctrl:1
	v_add_f32_dpp v75, v75, v75 quad_perm:[1,0,3,2] row_mask:0xf bank_mask:0xf bound_ctrl:1
	ds_read_b32 v32, v81 offset:10496
	v_add_f32_dpp v74, v74, v74 quad_perm:[2,3,0,1] row_mask:0xf bank_mask:0xf bound_ctrl:1
	v_add_f32_dpp v75, v75, v75 quad_perm:[2,3,0,1] row_mask:0xf bank_mask:0xf bound_ctrl:1
	ds_read_b32 v33, v82 offset:10496
	v_add_f32_dpp v76, v74, v74 row_half_mirror row_mask:0xf bank_mask:0xf bound_ctrl:1
	v_add_f32_dpp v64, v75, v75 row_half_mirror row_mask:0xf bank_mask:0xf bound_ctrl:1
	s_nop 0
	v_mov_b32_dpp v77, v76 row_ror:8 row_mask:0xf bank_mask:0xf bound_ctrl:1
	s_waitcnt lgkmcnt(9)
	v_pk_mul_f32 v[66:67], v[76:77], v[56:57] op_sel_hi:[1,0]
	v_pk_mul_f32 v[68:69], v[76:77], v[56:57] op_sel:[0,1]
	v_pk_mul_f32 v[70:71], v[76:77], v[58:59] op_sel_hi:[1,0]
	v_pk_mul_f32 v[72:73], v[76:77], v[58:59] op_sel:[0,1]
	v_pk_fma_f32 v[66:67], v[60:61], v[52:53], v[66:67] op_sel_hi:[1,0,1]
	v_pk_fma_f32 v[68:69], v[60:61], v[52:53], v[68:69] op_sel:[0,1,0]
	v_pk_fma_f32 v[70:71], v[60:61], v[54:55], v[70:71] op_sel_hi:[1,0,1]
	v_pk_fma_f32 v[72:73], v[60:61], v[54:55], v[72:73] op_sel:[0,1,0]
	v_pk_fma_f32 v[0:1], v[0:1], v[48:49], v[66:67] op_sel_hi:[1,0,1]
	v_pk_fma_f32 v[2:3], v[2:3], v[48:49], v[68:69] op_sel:[0,1,0]
	v_pk_fma_f32 v[4:5], v[4:5], v[50:51], v[70:71] op_sel_hi:[1,0,1]
	v_pk_fma_f32 v[6:7], v[6:7], v[50:51], v[72:73] op_sel:[0,1,0]
	ds_write_b32 v84, v64 offset:640
	ds_write_b32 v84, v76 offset:12928
	s_waitcnt lgkmcnt(7)
	v_pk_mul_f32 v[8:9], v[0:1], v[12:13] op_sel_hi:[1,0]
	v_pk_mul_f32 v[10:11], v[0:1], v[16:17] op_sel_hi:[1,0]
	ds_read_b128 v[40:43], v80 offset:11520
	v_pk_fma_f32 v[8:9], v[2:3], v[12:13], v[8:9] op_sel:[0,1,0]
	v_pk_fma_f32 v[10:11], v[2:3], v[16:17], v[10:11] op_sel:[0,1,0]
	ds_read_b128 v[44:47], v80 offset:10752
	v_pk_fma_f32 v[8:9], v[4:5], v[14:15], v[8:9] op_sel_hi:[1,0,1]
	v_pk_fma_f32 v[10:11], v[4:5], v[18:19], v[10:11] op_sel_hi:[1,0,1]
	ds_read_b128 v[48:51], v80 offset:11008
	v_pk_fma_f32 v[8:9], v[6:7], v[14:15], v[8:9] op_sel:[0,1,0]
	v_pk_fma_f32 v[10:11], v[6:7], v[18:19], v[10:11] op_sel:[0,1,0]
	ds_read_b128 v[52:55], v80 offset:11264
	v_add_f32_dpp v74, v9, v8 row_ror:8 row_mask:0xf bank_mask:0xf bound_ctrl:1
	v_add_f32_dpp v75, v11, v10 row_ror:8 row_mask:0xf bank_mask:0xf bound_ctrl:1
	ds_read_b128 v[56:59], v80 offset:11776
	v_add_f32_dpp v74, v74, v74 quad_perm:[1,0,3,2] row_mask:0xf bank_mask:0xf bound_ctrl:1
	v_add_f32_dpp v75, v75, v75 quad_perm:[1,0,3,2] row_mask:0xf bank_mask:0xf bound_ctrl:1
	ds_read_b32 v60, v81 offset:12032
	v_add_f32_dpp v74, v74, v74 quad_perm:[2,3,0,1] row_mask:0xf bank_mask:0xf bound_ctrl:1
	v_add_f32_dpp v75, v75, v75 quad_perm:[2,3,0,1] row_mask:0xf bank_mask:0xf bound_ctrl:1
	ds_read_b32 v61, v82 offset:12032
	v_add_f32_dpp v76, v74, v74 row_half_mirror row_mask:0xf bank_mask:0xf bound_ctrl:1
	v_add_f32_dpp v36, v75, v75 row_half_mirror row_mask:0xf bank_mask:0xf bound_ctrl:1
	s_nop 0
	v_mov_b32_dpp v77, v76 row_ror:8 row_mask:0xf bank_mask:0xf bound_ctrl:1
	s_waitcnt lgkmcnt(9)
	v_pk_mul_f32 v[66:67], v[76:77], v[28:29] op_sel_hi:[1,0]
	v_pk_mul_f32 v[68:69], v[76:77], v[28:29] op_sel:[0,1]
	v_pk_mul_f32 v[70:71], v[76:77], v[30:31] op_sel_hi:[1,0]
	v_pk_mul_f32 v[72:73], v[76:77], v[30:31] op_sel:[0,1]
	v_pk_fma_f32 v[66:67], v[32:33], v[24:25], v[66:67] op_sel_hi:[1,0,1]
	v_pk_fma_f32 v[68:69], v[32:33], v[24:25], v[68:69] op_sel:[0,1,0]
	v_pk_fma_f32 v[70:71], v[32:33], v[26:27], v[70:71] op_sel_hi:[1,0,1]
	v_pk_fma_f32 v[72:73], v[32:33], v[26:27], v[72:73] op_sel:[0,1,0]
	v_pk_fma_f32 v[0:1], v[0:1], v[20:21], v[66:67] op_sel_hi:[1,0,1]
	v_pk_fma_f32 v[2:3], v[2:3], v[20:21], v[68:69] op_sel:[0,1,0]
	v_pk_fma_f32 v[4:5], v[4:5], v[22:23], v[70:71] op_sel_hi:[1,0,1]
	v_pk_fma_f32 v[6:7], v[6:7], v[22:23], v[72:73] op_sel:[0,1,0]
	ds_write_b32 v84, v36 offset:768
	ds_write_b32 v84, v76 offset:13056
	s_waitcnt lgkmcnt(7)
	v_pk_mul_f32 v[8:9], v[0:1], v[40:41] op_sel_hi:[1,0]
	v_pk_mul_f32 v[10:11], v[0:1], v[44:45] op_sel_hi:[1,0]
	ds_read_b128 v[12:15], v80 offset:13056
	v_pk_fma_f32 v[8:9], v[2:3], v[40:41], v[8:9] op_sel:[0,1,0]
	v_pk_fma_f32 v[10:11], v[2:3], v[44:45], v[10:11] op_sel:[0,1,0]
	ds_read_b128 v[16:19], v80 offset:12288
	v_pk_fma_f32 v[8:9], v[4:5], v[42:43], v[8:9] op_sel_hi:[1,0,1]
	v_pk_fma_f32 v[10:11], v[4:5], v[46:47], v[10:11] op_sel_hi:[1,0,1]
	ds_read_b128 v[20:23], v80 offset:12544
	v_pk_fma_f32 v[8:9], v[6:7], v[42:43], v[8:9] op_sel:[0,1,0]
	v_pk_fma_f32 v[10:11], v[6:7], v[46:47], v[10:11] op_sel:[0,1,0]
	ds_read_b128 v[24:27], v80 offset:12800
	v_add_f32_dpp v74, v9, v8 row_ror:8 row_mask:0xf bank_mask:0xf bound_ctrl:1
	v_add_f32_dpp v75, v11, v10 row_ror:8 row_mask:0xf bank_mask:0xf bound_ctrl:1
	ds_read_b128 v[28:31], v80 offset:13312
	v_add_f32_dpp v74, v74, v74 quad_perm:[1,0,3,2] row_mask:0xf bank_mask:0xf bound_ctrl:1
	v_add_f32_dpp v75, v75, v75 quad_perm:[1,0,3,2] row_mask:0xf bank_mask:0xf bound_ctrl:1
	ds_read_b32 v32, v81 offset:13568
	v_add_f32_dpp v74, v74, v74 quad_perm:[2,3,0,1] row_mask:0xf bank_mask:0xf bound_ctrl:1
	v_add_f32_dpp v75, v75, v75 quad_perm:[2,3,0,1] row_mask:0xf bank_mask:0xf bound_ctrl:1
	ds_read_b32 v33, v82 offset:13568
	v_add_f32_dpp v76, v74, v74 row_half_mirror row_mask:0xf bank_mask:0xf bound_ctrl:1
	v_add_f32_dpp v64, v75, v75 row_half_mirror row_mask:0xf bank_mask:0xf bound_ctrl:1
	s_nop 0
	v_mov_b32_dpp v77, v76 row_ror:8 row_mask:0xf bank_mask:0xf bound_ctrl:1
	s_waitcnt lgkmcnt(9)
	v_pk_mul_f32 v[66:67], v[76:77], v[56:57] op_sel_hi:[1,0]
	v_pk_mul_f32 v[68:69], v[76:77], v[56:57] op_sel:[0,1]
	v_pk_mul_f32 v[70:71], v[76:77], v[58:59] op_sel_hi:[1,0]
	v_pk_mul_f32 v[72:73], v[76:77], v[58:59] op_sel:[0,1]
	v_pk_fma_f32 v[66:67], v[60:61], v[52:53], v[66:67] op_sel_hi:[1,0,1]
	v_pk_fma_f32 v[68:69], v[60:61], v[52:53], v[68:69] op_sel:[0,1,0]
	v_pk_fma_f32 v[70:71], v[60:61], v[54:55], v[70:71] op_sel_hi:[1,0,1]
	v_pk_fma_f32 v[72:73], v[60:61], v[54:55], v[72:73] op_sel:[0,1,0]
	v_pk_fma_f32 v[0:1], v[0:1], v[48:49], v[66:67] op_sel_hi:[1,0,1]
	v_pk_fma_f32 v[2:3], v[2:3], v[48:49], v[68:69] op_sel:[0,1,0]
	v_pk_fma_f32 v[4:5], v[4:5], v[50:51], v[70:71] op_sel_hi:[1,0,1]
	v_pk_fma_f32 v[6:7], v[6:7], v[50:51], v[72:73] op_sel:[0,1,0]
	ds_write_b32 v84, v64 offset:896
	ds_write_b32 v84, v76 offset:13184
	s_waitcnt lgkmcnt(7)
	v_pk_mul_f32 v[8:9], v[0:1], v[12:13] op_sel_hi:[1,0]
	v_pk_mul_f32 v[10:11], v[0:1], v[16:17] op_sel_hi:[1,0]
	ds_read_b128 v[40:43], v80 offset:14592
	v_pk_fma_f32 v[8:9], v[2:3], v[12:13], v[8:9] op_sel:[0,1,0]
	v_pk_fma_f32 v[10:11], v[2:3], v[16:17], v[10:11] op_sel:[0,1,0]
	ds_read_b128 v[44:47], v80 offset:13824
	v_pk_fma_f32 v[8:9], v[4:5], v[14:15], v[8:9] op_sel_hi:[1,0,1]
	v_pk_fma_f32 v[10:11], v[4:5], v[18:19], v[10:11] op_sel_hi:[1,0,1]
	ds_read_b128 v[48:51], v80 offset:14080
	v_pk_fma_f32 v[8:9], v[6:7], v[14:15], v[8:9] op_sel:[0,1,0]
	v_pk_fma_f32 v[10:11], v[6:7], v[18:19], v[10:11] op_sel:[0,1,0]
	ds_read_b128 v[52:55], v80 offset:14336
	v_add_f32_dpp v74, v9, v8 row_ror:8 row_mask:0xf bank_mask:0xf bound_ctrl:1
	v_add_f32_dpp v75, v11, v10 row_ror:8 row_mask:0xf bank_mask:0xf bound_ctrl:1
	ds_read_b128 v[56:59], v80 offset:14848
	v_add_f32_dpp v74, v74, v74 quad_perm:[1,0,3,2] row_mask:0xf bank_mask:0xf bound_ctrl:1
	v_add_f32_dpp v75, v75, v75 quad_perm:[1,0,3,2] row_mask:0xf bank_mask:0xf bound_ctrl:1
	ds_read_b32 v60, v81 offset:15104
	v_add_f32_dpp v74, v74, v74 quad_perm:[2,3,0,1] row_mask:0xf bank_mask:0xf bound_ctrl:1
	v_add_f32_dpp v75, v75, v75 quad_perm:[2,3,0,1] row_mask:0xf bank_mask:0xf bound_ctrl:1
	ds_read_b32 v61, v82 offset:15104
	v_add_f32_dpp v76, v74, v74 row_half_mirror row_mask:0xf bank_mask:0xf bound_ctrl:1
	v_add_f32_dpp v36, v75, v75 row_half_mirror row_mask:0xf bank_mask:0xf bound_ctrl:1
	s_nop 0
	v_mov_b32_dpp v77, v76 row_ror:8 row_mask:0xf bank_mask:0xf bound_ctrl:1
	s_waitcnt lgkmcnt(9)
	v_pk_mul_f32 v[66:67], v[76:77], v[28:29] op_sel_hi:[1,0]
	v_pk_mul_f32 v[68:69], v[76:77], v[28:29] op_sel:[0,1]
	v_pk_mul_f32 v[70:71], v[76:77], v[30:31] op_sel_hi:[1,0]
	v_pk_mul_f32 v[72:73], v[76:77], v[30:31] op_sel:[0,1]
	v_pk_fma_f32 v[66:67], v[32:33], v[24:25], v[66:67] op_sel_hi:[1,0,1]
	v_pk_fma_f32 v[68:69], v[32:33], v[24:25], v[68:69] op_sel:[0,1,0]
	v_pk_fma_f32 v[70:71], v[32:33], v[26:27], v[70:71] op_sel_hi:[1,0,1]
	v_pk_fma_f32 v[72:73], v[32:33], v[26:27], v[72:73] op_sel:[0,1,0]
	v_pk_fma_f32 v[0:1], v[0:1], v[20:21], v[66:67] op_sel_hi:[1,0,1]
	v_pk_fma_f32 v[2:3], v[2:3], v[20:21], v[68:69] op_sel:[0,1,0]
	v_pk_fma_f32 v[4:5], v[4:5], v[22:23], v[70:71] op_sel_hi:[1,0,1]
	v_pk_fma_f32 v[6:7], v[6:7], v[22:23], v[72:73] op_sel:[0,1,0]
	ds_write_b32 v84, v36 offset:1024
	ds_write_b32 v84, v76 offset:13312
	s_waitcnt lgkmcnt(7)
	v_pk_mul_f32 v[8:9], v[0:1], v[40:41] op_sel_hi:[1,0]
	v_pk_mul_f32 v[10:11], v[0:1], v[44:45] op_sel_hi:[1,0]
	ds_read_b128 v[12:15], v80 offset:16128
	v_pk_fma_f32 v[8:9], v[2:3], v[40:41], v[8:9] op_sel:[0,1,0]
	v_pk_fma_f32 v[10:11], v[2:3], v[44:45], v[10:11] op_sel:[0,1,0]
	ds_read_b128 v[16:19], v80 offset:15360
	v_pk_fma_f32 v[8:9], v[4:5], v[42:43], v[8:9] op_sel_hi:[1,0,1]
	v_pk_fma_f32 v[10:11], v[4:5], v[46:47], v[10:11] op_sel_hi:[1,0,1]
	ds_read_b128 v[20:23], v80 offset:15616
	v_pk_fma_f32 v[8:9], v[6:7], v[42:43], v[8:9] op_sel:[0,1,0]
	v_pk_fma_f32 v[10:11], v[6:7], v[46:47], v[10:11] op_sel:[0,1,0]
	ds_read_b128 v[24:27], v80 offset:15872
	v_add_f32_dpp v74, v9, v8 row_ror:8 row_mask:0xf bank_mask:0xf bound_ctrl:1
	v_add_f32_dpp v75, v11, v10 row_ror:8 row_mask:0xf bank_mask:0xf bound_ctrl:1
	ds_read_b128 v[28:31], v80 offset:16384
	v_add_f32_dpp v74, v74, v74 quad_perm:[1,0,3,2] row_mask:0xf bank_mask:0xf bound_ctrl:1
	v_add_f32_dpp v75, v75, v75 quad_perm:[1,0,3,2] row_mask:0xf bank_mask:0xf bound_ctrl:1
	ds_read_b32 v32, v81 offset:16640
	v_add_f32_dpp v74, v74, v74 quad_perm:[2,3,0,1] row_mask:0xf bank_mask:0xf bound_ctrl:1
	v_add_f32_dpp v75, v75, v75 quad_perm:[2,3,0,1] row_mask:0xf bank_mask:0xf bound_ctrl:1
	ds_read_b32 v33, v82 offset:16640
	v_add_f32_dpp v76, v74, v74 row_half_mirror row_mask:0xf bank_mask:0xf bound_ctrl:1
	v_add_f32_dpp v64, v75, v75 row_half_mirror row_mask:0xf bank_mask:0xf bound_ctrl:1
	s_nop 0
	v_mov_b32_dpp v77, v76 row_ror:8 row_mask:0xf bank_mask:0xf bound_ctrl:1
	s_waitcnt lgkmcnt(9)
	v_pk_mul_f32 v[66:67], v[76:77], v[56:57] op_sel_hi:[1,0]
	v_pk_mul_f32 v[68:69], v[76:77], v[56:57] op_sel:[0,1]
	v_pk_mul_f32 v[70:71], v[76:77], v[58:59] op_sel_hi:[1,0]
	v_pk_mul_f32 v[72:73], v[76:77], v[58:59] op_sel:[0,1]
	v_pk_fma_f32 v[66:67], v[60:61], v[52:53], v[66:67] op_sel_hi:[1,0,1]
	v_pk_fma_f32 v[68:69], v[60:61], v[52:53], v[68:69] op_sel:[0,1,0]
	v_pk_fma_f32 v[70:71], v[60:61], v[54:55], v[70:71] op_sel_hi:[1,0,1]
	v_pk_fma_f32 v[72:73], v[60:61], v[54:55], v[72:73] op_sel:[0,1,0]
	v_pk_fma_f32 v[0:1], v[0:1], v[48:49], v[66:67] op_sel_hi:[1,0,1]
	v_pk_fma_f32 v[2:3], v[2:3], v[48:49], v[68:69] op_sel:[0,1,0]
	v_pk_fma_f32 v[4:5], v[4:5], v[50:51], v[70:71] op_sel_hi:[1,0,1]
	v_pk_fma_f32 v[6:7], v[6:7], v[50:51], v[72:73] op_sel:[0,1,0]
	ds_write_b32 v84, v64 offset:1152
	ds_write_b32 v84, v76 offset:13440
	s_waitcnt lgkmcnt(7)
	v_pk_mul_f32 v[8:9], v[0:1], v[12:13] op_sel_hi:[1,0]
	v_pk_mul_f32 v[10:11], v[0:1], v[16:17] op_sel_hi:[1,0]
	ds_read_b128 v[40:43], v80 offset:17664
	v_pk_fma_f32 v[8:9], v[2:3], v[12:13], v[8:9] op_sel:[0,1,0]
	v_pk_fma_f32 v[10:11], v[2:3], v[16:17], v[10:11] op_sel:[0,1,0]
	ds_read_b128 v[44:47], v80 offset:16896
	v_pk_fma_f32 v[8:9], v[4:5], v[14:15], v[8:9] op_sel_hi:[1,0,1]
	v_pk_fma_f32 v[10:11], v[4:5], v[18:19], v[10:11] op_sel_hi:[1,0,1]
	ds_read_b128 v[48:51], v80 offset:17152
	v_pk_fma_f32 v[8:9], v[6:7], v[14:15], v[8:9] op_sel:[0,1,0]
	v_pk_fma_f32 v[10:11], v[6:7], v[18:19], v[10:11] op_sel:[0,1,0]
	ds_read_b128 v[52:55], v80 offset:17408
	v_add_f32_dpp v74, v9, v8 row_ror:8 row_mask:0xf bank_mask:0xf bound_ctrl:1
	v_add_f32_dpp v75, v11, v10 row_ror:8 row_mask:0xf bank_mask:0xf bound_ctrl:1
	ds_read_b128 v[56:59], v80 offset:17920
	v_add_f32_dpp v74, v74, v74 quad_perm:[1,0,3,2] row_mask:0xf bank_mask:0xf bound_ctrl:1
	v_add_f32_dpp v75, v75, v75 quad_perm:[1,0,3,2] row_mask:0xf bank_mask:0xf bound_ctrl:1
	ds_read_b32 v60, v81 offset:18176
	v_add_f32_dpp v74, v74, v74 quad_perm:[2,3,0,1] row_mask:0xf bank_mask:0xf bound_ctrl:1
	v_add_f32_dpp v75, v75, v75 quad_perm:[2,3,0,1] row_mask:0xf bank_mask:0xf bound_ctrl:1
	ds_read_b32 v61, v82 offset:18176
	v_add_f32_dpp v76, v74, v74 row_half_mirror row_mask:0xf bank_mask:0xf bound_ctrl:1
	v_add_f32_dpp v36, v75, v75 row_half_mirror row_mask:0xf bank_mask:0xf bound_ctrl:1
	s_nop 0
	v_mov_b32_dpp v77, v76 row_ror:8 row_mask:0xf bank_mask:0xf bound_ctrl:1
	s_waitcnt lgkmcnt(9)
	v_pk_mul_f32 v[66:67], v[76:77], v[28:29] op_sel_hi:[1,0]
	v_pk_mul_f32 v[68:69], v[76:77], v[28:29] op_sel:[0,1]
	v_pk_mul_f32 v[70:71], v[76:77], v[30:31] op_sel_hi:[1,0]
	v_pk_mul_f32 v[72:73], v[76:77], v[30:31] op_sel:[0,1]
	v_pk_fma_f32 v[66:67], v[32:33], v[24:25], v[66:67] op_sel_hi:[1,0,1]
	v_pk_fma_f32 v[68:69], v[32:33], v[24:25], v[68:69] op_sel:[0,1,0]
	v_pk_fma_f32 v[70:71], v[32:33], v[26:27], v[70:71] op_sel_hi:[1,0,1]
	v_pk_fma_f32 v[72:73], v[32:33], v[26:27], v[72:73] op_sel:[0,1,0]
	v_pk_fma_f32 v[0:1], v[0:1], v[20:21], v[66:67] op_sel_hi:[1,0,1]
	v_pk_fma_f32 v[2:3], v[2:3], v[20:21], v[68:69] op_sel:[0,1,0]
	v_pk_fma_f32 v[4:5], v[4:5], v[22:23], v[70:71] op_sel_hi:[1,0,1]
	v_pk_fma_f32 v[6:7], v[6:7], v[22:23], v[72:73] op_sel:[0,1,0]
	ds_write_b32 v84, v36 offset:1280
	ds_write_b32 v84, v76 offset:13568
	s_waitcnt lgkmcnt(7)
	v_pk_mul_f32 v[8:9], v[0:1], v[40:41] op_sel_hi:[1,0]
	v_pk_mul_f32 v[10:11], v[0:1], v[44:45] op_sel_hi:[1,0]
	ds_read_b128 v[12:15], v80 offset:19200
	v_pk_fma_f32 v[8:9], v[2:3], v[40:41], v[8:9] op_sel:[0,1,0]
	v_pk_fma_f32 v[10:11], v[2:3], v[44:45], v[10:11] op_sel:[0,1,0]
	ds_read_b128 v[16:19], v80 offset:18432
	v_pk_fma_f32 v[8:9], v[4:5], v[42:43], v[8:9] op_sel_hi:[1,0,1]
	v_pk_fma_f32 v[10:11], v[4:5], v[46:47], v[10:11] op_sel_hi:[1,0,1]
	ds_read_b128 v[20:23], v80 offset:18688
	v_pk_fma_f32 v[8:9], v[6:7], v[42:43], v[8:9] op_sel:[0,1,0]
	v_pk_fma_f32 v[10:11], v[6:7], v[46:47], v[10:11] op_sel:[0,1,0]
	ds_read_b128 v[24:27], v80 offset:18944
	v_add_f32_dpp v74, v9, v8 row_ror:8 row_mask:0xf bank_mask:0xf bound_ctrl:1
	v_add_f32_dpp v75, v11, v10 row_ror:8 row_mask:0xf bank_mask:0xf bound_ctrl:1
	ds_read_b128 v[28:31], v80 offset:19456
	v_add_f32_dpp v74, v74, v74 quad_perm:[1,0,3,2] row_mask:0xf bank_mask:0xf bound_ctrl:1
	v_add_f32_dpp v75, v75, v75 quad_perm:[1,0,3,2] row_mask:0xf bank_mask:0xf bound_ctrl:1
	ds_read_b32 v32, v81 offset:19712
	v_add_f32_dpp v74, v74, v74 quad_perm:[2,3,0,1] row_mask:0xf bank_mask:0xf bound_ctrl:1
	v_add_f32_dpp v75, v75, v75 quad_perm:[2,3,0,1] row_mask:0xf bank_mask:0xf bound_ctrl:1
	ds_read_b32 v33, v82 offset:19712
	v_add_f32_dpp v76, v74, v74 row_half_mirror row_mask:0xf bank_mask:0xf bound_ctrl:1
	v_add_f32_dpp v64, v75, v75 row_half_mirror row_mask:0xf bank_mask:0xf bound_ctrl:1
	s_nop 0
	v_mov_b32_dpp v77, v76 row_ror:8 row_mask:0xf bank_mask:0xf bound_ctrl:1
	s_waitcnt lgkmcnt(9)
	v_pk_mul_f32 v[66:67], v[76:77], v[56:57] op_sel_hi:[1,0]
	v_pk_mul_f32 v[68:69], v[76:77], v[56:57] op_sel:[0,1]
	v_pk_mul_f32 v[70:71], v[76:77], v[58:59] op_sel_hi:[1,0]
	v_pk_mul_f32 v[72:73], v[76:77], v[58:59] op_sel:[0,1]
	v_pk_fma_f32 v[66:67], v[60:61], v[52:53], v[66:67] op_sel_hi:[1,0,1]
	v_pk_fma_f32 v[68:69], v[60:61], v[52:53], v[68:69] op_sel:[0,1,0]
	v_pk_fma_f32 v[70:71], v[60:61], v[54:55], v[70:71] op_sel_hi:[1,0,1]
	v_pk_fma_f32 v[72:73], v[60:61], v[54:55], v[72:73] op_sel:[0,1,0]
	v_pk_fma_f32 v[0:1], v[0:1], v[48:49], v[66:67] op_sel_hi:[1,0,1]
	v_pk_fma_f32 v[2:3], v[2:3], v[48:49], v[68:69] op_sel:[0,1,0]
	v_pk_fma_f32 v[4:5], v[4:5], v[50:51], v[70:71] op_sel_hi:[1,0,1]
	v_pk_fma_f32 v[6:7], v[6:7], v[50:51], v[72:73] op_sel:[0,1,0]
	ds_write_b32 v84, v64 offset:1408
	ds_write_b32 v84, v76 offset:13696
	s_waitcnt lgkmcnt(7)
	v_pk_mul_f32 v[8:9], v[0:1], v[12:13] op_sel_hi:[1,0]
	v_pk_mul_f32 v[10:11], v[0:1], v[16:17] op_sel_hi:[1,0]
	ds_read_b128 v[40:43], v80 offset:20736
	v_pk_fma_f32 v[8:9], v[2:3], v[12:13], v[8:9] op_sel:[0,1,0]
	v_pk_fma_f32 v[10:11], v[2:3], v[16:17], v[10:11] op_sel:[0,1,0]
	ds_read_b128 v[44:47], v80 offset:19968
	v_pk_fma_f32 v[8:9], v[4:5], v[14:15], v[8:9] op_sel_hi:[1,0,1]
	v_pk_fma_f32 v[10:11], v[4:5], v[18:19], v[10:11] op_sel_hi:[1,0,1]
	ds_read_b128 v[48:51], v80 offset:20224
	v_pk_fma_f32 v[8:9], v[6:7], v[14:15], v[8:9] op_sel:[0,1,0]
	v_pk_fma_f32 v[10:11], v[6:7], v[18:19], v[10:11] op_sel:[0,1,0]
	ds_read_b128 v[52:55], v80 offset:20480
	v_add_f32_dpp v74, v9, v8 row_ror:8 row_mask:0xf bank_mask:0xf bound_ctrl:1
	v_add_f32_dpp v75, v11, v10 row_ror:8 row_mask:0xf bank_mask:0xf bound_ctrl:1
	ds_read_b128 v[56:59], v80 offset:20992
	v_add_f32_dpp v74, v74, v74 quad_perm:[1,0,3,2] row_mask:0xf bank_mask:0xf bound_ctrl:1
	v_add_f32_dpp v75, v75, v75 quad_perm:[1,0,3,2] row_mask:0xf bank_mask:0xf bound_ctrl:1
	ds_read_b32 v60, v81 offset:21248
	v_add_f32_dpp v74, v74, v74 quad_perm:[2,3,0,1] row_mask:0xf bank_mask:0xf bound_ctrl:1
	v_add_f32_dpp v75, v75, v75 quad_perm:[2,3,0,1] row_mask:0xf bank_mask:0xf bound_ctrl:1
	ds_read_b32 v61, v82 offset:21248
	v_add_f32_dpp v76, v74, v74 row_half_mirror row_mask:0xf bank_mask:0xf bound_ctrl:1
	v_add_f32_dpp v36, v75, v75 row_half_mirror row_mask:0xf bank_mask:0xf bound_ctrl:1
	s_nop 0
	v_mov_b32_dpp v77, v76 row_ror:8 row_mask:0xf bank_mask:0xf bound_ctrl:1
	s_waitcnt lgkmcnt(9)
	v_pk_mul_f32 v[66:67], v[76:77], v[28:29] op_sel_hi:[1,0]
	v_pk_mul_f32 v[68:69], v[76:77], v[28:29] op_sel:[0,1]
	v_pk_mul_f32 v[70:71], v[76:77], v[30:31] op_sel_hi:[1,0]
	v_pk_mul_f32 v[72:73], v[76:77], v[30:31] op_sel:[0,1]
	v_pk_fma_f32 v[66:67], v[32:33], v[24:25], v[66:67] op_sel_hi:[1,0,1]
	v_pk_fma_f32 v[68:69], v[32:33], v[24:25], v[68:69] op_sel:[0,1,0]
	v_pk_fma_f32 v[70:71], v[32:33], v[26:27], v[70:71] op_sel_hi:[1,0,1]
	v_pk_fma_f32 v[72:73], v[32:33], v[26:27], v[72:73] op_sel:[0,1,0]
	v_pk_fma_f32 v[0:1], v[0:1], v[20:21], v[66:67] op_sel_hi:[1,0,1]
	v_pk_fma_f32 v[2:3], v[2:3], v[20:21], v[68:69] op_sel:[0,1,0]
	v_pk_fma_f32 v[4:5], v[4:5], v[22:23], v[70:71] op_sel_hi:[1,0,1]
	v_pk_fma_f32 v[6:7], v[6:7], v[22:23], v[72:73] op_sel:[0,1,0]
	ds_write_b32 v84, v36 offset:1536
	ds_write_b32 v84, v76 offset:13824
	s_waitcnt lgkmcnt(7)
	v_pk_mul_f32 v[8:9], v[0:1], v[40:41] op_sel_hi:[1,0]
	v_pk_mul_f32 v[10:11], v[0:1], v[44:45] op_sel_hi:[1,0]
	ds_read_b128 v[12:15], v80 offset:22272
	v_pk_fma_f32 v[8:9], v[2:3], v[40:41], v[8:9] op_sel:[0,1,0]
	v_pk_fma_f32 v[10:11], v[2:3], v[44:45], v[10:11] op_sel:[0,1,0]
	ds_read_b128 v[16:19], v80 offset:21504
	v_pk_fma_f32 v[8:9], v[4:5], v[42:43], v[8:9] op_sel_hi:[1,0,1]
	v_pk_fma_f32 v[10:11], v[4:5], v[46:47], v[10:11] op_sel_hi:[1,0,1]
	ds_read_b128 v[20:23], v80 offset:21760
	v_pk_fma_f32 v[8:9], v[6:7], v[42:43], v[8:9] op_sel:[0,1,0]
	v_pk_fma_f32 v[10:11], v[6:7], v[46:47], v[10:11] op_sel:[0,1,0]
	ds_read_b128 v[24:27], v80 offset:22016
	v_add_f32_dpp v74, v9, v8 row_ror:8 row_mask:0xf bank_mask:0xf bound_ctrl:1
	v_add_f32_dpp v75, v11, v10 row_ror:8 row_mask:0xf bank_mask:0xf bound_ctrl:1
	ds_read_b128 v[28:31], v80 offset:22528
	v_add_f32_dpp v74, v74, v74 quad_perm:[1,0,3,2] row_mask:0xf bank_mask:0xf bound_ctrl:1
	v_add_f32_dpp v75, v75, v75 quad_perm:[1,0,3,2] row_mask:0xf bank_mask:0xf bound_ctrl:1
	ds_read_b32 v32, v81 offset:22784
	v_add_f32_dpp v74, v74, v74 quad_perm:[2,3,0,1] row_mask:0xf bank_mask:0xf bound_ctrl:1
	v_add_f32_dpp v75, v75, v75 quad_perm:[2,3,0,1] row_mask:0xf bank_mask:0xf bound_ctrl:1
	ds_read_b32 v33, v82 offset:22784
	v_add_f32_dpp v76, v74, v74 row_half_mirror row_mask:0xf bank_mask:0xf bound_ctrl:1
	v_add_f32_dpp v64, v75, v75 row_half_mirror row_mask:0xf bank_mask:0xf bound_ctrl:1
	s_nop 0
	v_mov_b32_dpp v77, v76 row_ror:8 row_mask:0xf bank_mask:0xf bound_ctrl:1
	s_waitcnt lgkmcnt(9)
	v_pk_mul_f32 v[66:67], v[76:77], v[56:57] op_sel_hi:[1,0]
	v_pk_mul_f32 v[68:69], v[76:77], v[56:57] op_sel:[0,1]
	v_pk_mul_f32 v[70:71], v[76:77], v[58:59] op_sel_hi:[1,0]
	v_pk_mul_f32 v[72:73], v[76:77], v[58:59] op_sel:[0,1]
	v_pk_fma_f32 v[66:67], v[60:61], v[52:53], v[66:67] op_sel_hi:[1,0,1]
	v_pk_fma_f32 v[68:69], v[60:61], v[52:53], v[68:69] op_sel:[0,1,0]
	v_pk_fma_f32 v[70:71], v[60:61], v[54:55], v[70:71] op_sel_hi:[1,0,1]
	v_pk_fma_f32 v[72:73], v[60:61], v[54:55], v[72:73] op_sel:[0,1,0]
	v_pk_fma_f32 v[0:1], v[0:1], v[48:49], v[66:67] op_sel_hi:[1,0,1]
	v_pk_fma_f32 v[2:3], v[2:3], v[48:49], v[68:69] op_sel:[0,1,0]
	v_pk_fma_f32 v[4:5], v[4:5], v[50:51], v[70:71] op_sel_hi:[1,0,1]
	v_pk_fma_f32 v[6:7], v[6:7], v[50:51], v[72:73] op_sel:[0,1,0]
	ds_write_b32 v84, v64 offset:1664
	ds_write_b32 v84, v76 offset:13952
	s_waitcnt lgkmcnt(7)
	v_pk_mul_f32 v[8:9], v[0:1], v[12:13] op_sel_hi:[1,0]
	v_pk_mul_f32 v[10:11], v[0:1], v[16:17] op_sel_hi:[1,0]
	ds_read_b128 v[40:43], v80 offset:23808
	v_pk_fma_f32 v[8:9], v[2:3], v[12:13], v[8:9] op_sel:[0,1,0]
	v_pk_fma_f32 v[10:11], v[2:3], v[16:17], v[10:11] op_sel:[0,1,0]
	ds_read_b128 v[44:47], v80 offset:23040
	v_pk_fma_f32 v[8:9], v[4:5], v[14:15], v[8:9] op_sel_hi:[1,0,1]
	v_pk_fma_f32 v[10:11], v[4:5], v[18:19], v[10:11] op_sel_hi:[1,0,1]
	ds_read_b128 v[48:51], v80 offset:23296
	v_pk_fma_f32 v[8:9], v[6:7], v[14:15], v[8:9] op_sel:[0,1,0]
	v_pk_fma_f32 v[10:11], v[6:7], v[18:19], v[10:11] op_sel:[0,1,0]
	ds_read_b128 v[52:55], v80 offset:23552
	v_add_f32_dpp v74, v9, v8 row_ror:8 row_mask:0xf bank_mask:0xf bound_ctrl:1
	v_add_f32_dpp v75, v11, v10 row_ror:8 row_mask:0xf bank_mask:0xf bound_ctrl:1
	ds_read_b128 v[56:59], v80 offset:24064
	v_add_f32_dpp v74, v74, v74 quad_perm:[1,0,3,2] row_mask:0xf bank_mask:0xf bound_ctrl:1
	v_add_f32_dpp v75, v75, v75 quad_perm:[1,0,3,2] row_mask:0xf bank_mask:0xf bound_ctrl:1
	ds_read_b32 v60, v81 offset:24320
	v_add_f32_dpp v74, v74, v74 quad_perm:[2,3,0,1] row_mask:0xf bank_mask:0xf bound_ctrl:1
	v_add_f32_dpp v75, v75, v75 quad_perm:[2,3,0,1] row_mask:0xf bank_mask:0xf bound_ctrl:1
	ds_read_b32 v61, v82 offset:24320
	v_add_f32_dpp v76, v74, v74 row_half_mirror row_mask:0xf bank_mask:0xf bound_ctrl:1
	v_add_f32_dpp v36, v75, v75 row_half_mirror row_mask:0xf bank_mask:0xf bound_ctrl:1
	s_nop 0
	v_mov_b32_dpp v77, v76 row_ror:8 row_mask:0xf bank_mask:0xf bound_ctrl:1
	s_waitcnt lgkmcnt(9)
	v_pk_mul_f32 v[66:67], v[76:77], v[28:29] op_sel_hi:[1,0]
	v_pk_mul_f32 v[68:69], v[76:77], v[28:29] op_sel:[0,1]
	v_pk_mul_f32 v[70:71], v[76:77], v[30:31] op_sel_hi:[1,0]
	v_pk_mul_f32 v[72:73], v[76:77], v[30:31] op_sel:[0,1]
	v_pk_fma_f32 v[66:67], v[32:33], v[24:25], v[66:67] op_sel_hi:[1,0,1]
	v_pk_fma_f32 v[68:69], v[32:33], v[24:25], v[68:69] op_sel:[0,1,0]
	v_pk_fma_f32 v[70:71], v[32:33], v[26:27], v[70:71] op_sel_hi:[1,0,1]
	v_pk_fma_f32 v[72:73], v[32:33], v[26:27], v[72:73] op_sel:[0,1,0]
	v_pk_fma_f32 v[0:1], v[0:1], v[20:21], v[66:67] op_sel_hi:[1,0,1]
	v_pk_fma_f32 v[2:3], v[2:3], v[20:21], v[68:69] op_sel:[0,1,0]
	v_pk_fma_f32 v[4:5], v[4:5], v[22:23], v[70:71] op_sel_hi:[1,0,1]
	v_pk_fma_f32 v[6:7], v[6:7], v[22:23], v[72:73] op_sel:[0,1,0]
	ds_write_b32 v84, v36 offset:1792
	ds_write_b32 v84, v76 offset:14080
	s_waitcnt lgkmcnt(7)
	v_pk_mul_f32 v[8:9], v[0:1], v[40:41] op_sel_hi:[1,0]
	v_pk_mul_f32 v[10:11], v[0:1], v[44:45] op_sel_hi:[1,0]
	ds_read_b128 v[12:15], v80 offset:25344
	v_pk_fma_f32 v[8:9], v[2:3], v[40:41], v[8:9] op_sel:[0,1,0]
	v_pk_fma_f32 v[10:11], v[2:3], v[44:45], v[10:11] op_sel:[0,1,0]
	ds_read_b128 v[16:19], v80 offset:24576
	v_pk_fma_f32 v[8:9], v[4:5], v[42:43], v[8:9] op_sel_hi:[1,0,1]
	v_pk_fma_f32 v[10:11], v[4:5], v[46:47], v[10:11] op_sel_hi:[1,0,1]
	ds_read_b128 v[20:23], v80 offset:24832
	v_pk_fma_f32 v[8:9], v[6:7], v[42:43], v[8:9] op_sel:[0,1,0]
	v_pk_fma_f32 v[10:11], v[6:7], v[46:47], v[10:11] op_sel:[0,1,0]
	ds_read_b128 v[24:27], v80 offset:25088
	v_add_f32_dpp v74, v9, v8 row_ror:8 row_mask:0xf bank_mask:0xf bound_ctrl:1
	v_add_f32_dpp v75, v11, v10 row_ror:8 row_mask:0xf bank_mask:0xf bound_ctrl:1
	ds_read_b128 v[28:31], v80 offset:25600
	v_add_f32_dpp v74, v74, v74 quad_perm:[1,0,3,2] row_mask:0xf bank_mask:0xf bound_ctrl:1
	v_add_f32_dpp v75, v75, v75 quad_perm:[1,0,3,2] row_mask:0xf bank_mask:0xf bound_ctrl:1
	ds_read_b32 v32, v81 offset:25856
	v_add_f32_dpp v74, v74, v74 quad_perm:[2,3,0,1] row_mask:0xf bank_mask:0xf bound_ctrl:1
	v_add_f32_dpp v75, v75, v75 quad_perm:[2,3,0,1] row_mask:0xf bank_mask:0xf bound_ctrl:1
	ds_read_b32 v33, v82 offset:25856
	v_add_f32_dpp v76, v74, v74 row_half_mirror row_mask:0xf bank_mask:0xf bound_ctrl:1
	v_add_f32_dpp v64, v75, v75 row_half_mirror row_mask:0xf bank_mask:0xf bound_ctrl:1
	s_nop 0
	v_mov_b32_dpp v77, v76 row_ror:8 row_mask:0xf bank_mask:0xf bound_ctrl:1
	s_waitcnt lgkmcnt(9)
	v_pk_mul_f32 v[66:67], v[76:77], v[56:57] op_sel_hi:[1,0]
	v_pk_mul_f32 v[68:69], v[76:77], v[56:57] op_sel:[0,1]
	v_pk_mul_f32 v[70:71], v[76:77], v[58:59] op_sel_hi:[1,0]
	v_pk_mul_f32 v[72:73], v[76:77], v[58:59] op_sel:[0,1]
	v_pk_fma_f32 v[66:67], v[60:61], v[52:53], v[66:67] op_sel_hi:[1,0,1]
	v_pk_fma_f32 v[68:69], v[60:61], v[52:53], v[68:69] op_sel:[0,1,0]
	v_pk_fma_f32 v[70:71], v[60:61], v[54:55], v[70:71] op_sel_hi:[1,0,1]
	v_pk_fma_f32 v[72:73], v[60:61], v[54:55], v[72:73] op_sel:[0,1,0]
	v_pk_fma_f32 v[0:1], v[0:1], v[48:49], v[66:67] op_sel_hi:[1,0,1]
	v_pk_fma_f32 v[2:3], v[2:3], v[48:49], v[68:69] op_sel:[0,1,0]
	v_pk_fma_f32 v[4:5], v[4:5], v[50:51], v[70:71] op_sel_hi:[1,0,1]
	v_pk_fma_f32 v[6:7], v[6:7], v[50:51], v[72:73] op_sel:[0,1,0]
	ds_write_b32 v84, v64 offset:1920
	ds_write_b32 v84, v76 offset:14208
	s_cmp_eq_u32 s4, 64
	s_cbranch_scc1 .Lrec_chunk_end
	s_waitcnt lgkmcnt(7)
	v_pk_mul_f32 v[8:9], v[0:1], v[12:13] op_sel_hi:[1,0]
	v_pk_mul_f32 v[10:11], v[0:1], v[16:17] op_sel_hi:[1,0]
	ds_read_b128 v[40:43], v80 offset:26880
	v_pk_fma_f32 v[8:9], v[2:3], v[12:13], v[8:9] op_sel:[0,1,0]
	v_pk_fma_f32 v[10:11], v[2:3], v[16:17], v[10:11] op_sel:[0,1,0]
	ds_read_b128 v[44:47], v80 offset:26112
	v_pk_fma_f32 v[8:9], v[4:5], v[14:15], v[8:9] op_sel_hi:[1,0,1]
	v_pk_fma_f32 v[10:11], v[4:5], v[18:19], v[10:11] op_sel_hi:[1,0,1]
	ds_read_b128 v[48:51], v80 offset:26368
	v_pk_fma_f32 v[8:9], v[6:7], v[14:15], v[8:9] op_sel:[0,1,0]
	v_pk_fma_f32 v[10:11], v[6:7], v[18:19], v[10:11] op_sel:[0,1,0]
	ds_read_b128 v[52:55], v80 offset:26624
	v_add_f32_dpp v74, v9, v8 row_ror:8 row_mask:0xf bank_mask:0xf bound_ctrl:1
	v_add_f32_dpp v75, v11, v10 row_ror:8 row_mask:0xf bank_mask:0xf bound_ctrl:1
	ds_read_b128 v[56:59], v80 offset:27136
	v_add_f32_dpp v74, v74, v74 quad_perm:[1,0,3,2] row_mask:0xf bank_mask:0xf bound_ctrl:1
	v_add_f32_dpp v75, v75, v75 quad_perm:[1,0,3,2] row_mask:0xf bank_mask:0xf bound_ctrl:1
	ds_read_b32 v60, v81 offset:27392
	v_add_f32_dpp v74, v74, v74 quad_perm:[2,3,0,1] row_mask:0xf bank_mask:0xf bound_ctrl:1
	v_add_f32_dpp v75, v75, v75 quad_perm:[2,3,0,1] row_mask:0xf bank_mask:0xf bound_ctrl:1
	ds_read_b32 v61, v82 offset:27392
	v_add_f32_dpp v76, v74, v74 row_half_mirror row_mask:0xf bank_mask:0xf bound_ctrl:1
	v_add_f32_dpp v36, v75, v75 row_half_mirror row_mask:0xf bank_mask:0xf bound_ctrl:1
	s_nop 0
	v_mov_b32_dpp v77, v76 row_ror:8 row_mask:0xf bank_mask:0xf bound_ctrl:1
	s_waitcnt lgkmcnt(9)
	v_pk_mul_f32 v[66:67], v[76:77], v[28:29] op_sel_hi:[1,0]
	v_pk_mul_f32 v[68:69], v[76:77], v[28:29] op_sel:[0,1]
	v_pk_mul_f32 v[70:71], v[76:77], v[30:31] op_sel_hi:[1,0]
	v_pk_mul_f32 v[72:73], v[76:77], v[30:31] op_sel:[0,1]
	v_pk_fma_f32 v[66:67], v[32:33], v[24:25], v[66:67] op_sel_hi:[1,0,1]
	v_pk_fma_f32 v[68:69], v[32:33], v[24:25], v[68:69] op_sel:[0,1,0]
	v_pk_fma_f32 v[70:71], v[32:33], v[26:27], v[70:71] op_sel_hi:[1,0,1]
	v_pk_fma_f32 v[72:73], v[32:33], v[26:27], v[72:73] op_sel:[0,1,0]
	v_pk_fma_f32 v[0:1], v[0:1], v[20:21], v[66:67] op_sel_hi:[1,0,1]
	v_pk_fma_f32 v[2:3], v[2:3], v[20:21], v[68:69] op_sel:[0,1,0]
	v_pk_fma_f32 v[4:5], v[4:5], v[22:23], v[70:71] op_sel_hi:[1,0,1]
	v_pk_fma_f32 v[6:7], v[6:7], v[22:23], v[72:73] op_sel:[0,1,0]
	ds_write_b32 v84, v36 offset:2048
	ds_write_b32 v84, v76 offset:14336
	s_waitcnt lgkmcnt(7)
	v_pk_mul_f32 v[8:9], v[0:1], v[40:41] op_sel_hi:[1,0]
	v_pk_mul_f32 v[10:11], v[0:1], v[44:45] op_sel_hi:[1,0]
	ds_read_b128 v[12:15], v80 offset:28416
	v_pk_fma_f32 v[8:9], v[2:3], v[40:41], v[8:9] op_sel:[0,1,0]
	v_pk_fma_f32 v[10:11], v[2:3], v[44:45], v[10:11] op_sel:[0,1,0]
	ds_read_b128 v[16:19], v80 offset:27648
	v_pk_fma_f32 v[8:9], v[4:5], v[42:43], v[8:9] op_sel_hi:[1,0,1]
	v_pk_fma_f32 v[10:11], v[4:5], v[46:47], v[10:11] op_sel_hi:[1,0,1]
	ds_read_b128 v[20:23], v80 offset:27904
	v_pk_fma_f32 v[8:9], v[6:7], v[42:43], v[8:9] op_sel:[0,1,0]
	v_pk_fma_f32 v[10:11], v[6:7], v[46:47], v[10:11] op_sel:[0,1,0]
	ds_read_b128 v[24:27], v80 offset:28160
	v_add_f32_dpp v74, v9, v8 row_ror:8 row_mask:0xf bank_mask:0xf bound_ctrl:1
	v_add_f32_dpp v75, v11, v10 row_ror:8 row_mask:0xf bank_mask:0xf bound_ctrl:1
	ds_read_b128 v[28:31], v80 offset:28672
	v_add_f32_dpp v74, v74, v74 quad_perm:[1,0,3,2] row_mask:0xf bank_mask:0xf bound_ctrl:1
	v_add_f32_dpp v75, v75, v75 quad_perm:[1,0,3,2] row_mask:0xf bank_mask:0xf bound_ctrl:1
	ds_read_b32 v32, v81 offset:28928
	v_add_f32_dpp v74, v74, v74 quad_perm:[2,3,0,1] row_mask:0xf bank_mask:0xf bound_ctrl:1
	v_add_f32_dpp v75, v75, v75 quad_perm:[2,3,0,1] row_mask:0xf bank_mask:0xf bound_ctrl:1
	ds_read_b32 v33, v82 offset:28928
	v_add_f32_dpp v76, v74, v74 row_half_mirror row_mask:0xf bank_mask:0xf bound_ctrl:1
	v_add_f32_dpp v64, v75, v75 row_half_mirror row_mask:0xf bank_mask:0xf bound_ctrl:1
	s_nop 0
	v_mov_b32_dpp v77, v76 row_ror:8 row_mask:0xf bank_mask:0xf bound_ctrl:1
	s_waitcnt lgkmcnt(9)
	v_pk_mul_f32 v[66:67], v[76:77], v[56:57] op_sel_hi:[1,0]
	v_pk_mul_f32 v[68:69], v[76:77], v[56:57] op_sel:[0,1]
	v_pk_mul_f32 v[70:71], v[76:77], v[58:59] op_sel_hi:[1,0]
	v_pk_mul_f32 v[72:73], v[76:77], v[58:59] op_sel:[0,1]
	v_pk_fma_f32 v[66:67], v[60:61], v[52:53], v[66:67] op_sel_hi:[1,0,1]
	v_pk_fma_f32 v[68:69], v[60:61], v[52:53], v[68:69] op_sel:[0,1,0]
	v_pk_fma_f32 v[70:71], v[60:61], v[54:55], v[70:71] op_sel_hi:[1,0,1]
	v_pk_fma_f32 v[72:73], v[60:61], v[54:55], v[72:73] op_sel:[0,1,0]
	v_pk_fma_f32 v[0:1], v[0:1], v[48:49], v[66:67] op_sel_hi:[1,0,1]
	v_pk_fma_f32 v[2:3], v[2:3], v[48:49], v[68:69] op_sel:[0,1,0]
	v_pk_fma_f32 v[4:5], v[4:5], v[50:51], v[70:71] op_sel_hi:[1,0,1]
	v_pk_fma_f32 v[6:7], v[6:7], v[50:51], v[72:73] op_sel:[0,1,0]
	ds_write_b32 v84, v64 offset:2176
	ds_write_b32 v84, v76 offset:14464
	s_waitcnt lgkmcnt(7)
	v_pk_mul_f32 v[8:9], v[0:1], v[12:13] op_sel_hi:[1,0]
	v_pk_mul_f32 v[10:11], v[0:1], v[16:17] op_sel_hi:[1,0]
	ds_read_b128 v[40:43], v80 offset:29952
	v_pk_fma_f32 v[8:9], v[2:3], v[12:13], v[8:9] op_sel:[0,1,0]
	v_pk_fma_f32 v[10:11], v[2:3], v[16:17], v[10:11] op_sel:[0,1,0]
	ds_read_b128 v[44:47], v80 offset:29184
	v_pk_fma_f32 v[8:9], v[4:5], v[14:15], v[8:9] op_sel_hi:[1,0,1]
	v_pk_fma_f32 v[10:11], v[4:5], v[18:19], v[10:11] op_sel_hi:[1,0,1]
	ds_read_b128 v[48:51], v80 offset:29440
	v_pk_fma_f32 v[8:9], v[6:7], v[14:15], v[8:9] op_sel:[0,1,0]
	v_pk_fma_f32 v[10:11], v[6:7], v[18:19], v[10:11] op_sel:[0,1,0]
	ds_read_b128 v[52:55], v80 offset:29696
	v_add_f32_dpp v74, v9, v8 row_ror:8 row_mask:0xf bank_mask:0xf bound_ctrl:1
	v_add_f32_dpp v75, v11, v10 row_ror:8 row_mask:0xf bank_mask:0xf bound_ctrl:1
	ds_read_b128 v[56:59], v80 offset:30208
	v_add_f32_dpp v74, v74, v74 quad_perm:[1,0,3,2] row_mask:0xf bank_mask:0xf bound_ctrl:1
	v_add_f32_dpp v75, v75, v75 quad_perm:[1,0,3,2] row_mask:0xf bank_mask:0xf bound_ctrl:1
	ds_read_b32 v60, v81 offset:30464
	v_add_f32_dpp v74, v74, v74 quad_perm:[2,3,0,1] row_mask:0xf bank_mask:0xf bound_ctrl:1
	v_add_f32_dpp v75, v75, v75 quad_perm:[2,3,0,1] row_mask:0xf bank_mask:0xf bound_ctrl:1
	ds_read_b32 v61, v82 offset:30464
	v_add_f32_dpp v76, v74, v74 row_half_mirror row_mask:0xf bank_mask:0xf bound_ctrl:1
	v_add_f32_dpp v36, v75, v75 row_half_mirror row_mask:0xf bank_mask:0xf bound_ctrl:1
	s_nop 0
	v_mov_b32_dpp v77, v76 row_ror:8 row_mask:0xf bank_mask:0xf bound_ctrl:1
	s_waitcnt lgkmcnt(9)
	v_pk_mul_f32 v[66:67], v[76:77], v[28:29] op_sel_hi:[1,0]
	v_pk_mul_f32 v[68:69], v[76:77], v[28:29] op_sel:[0,1]
	v_pk_mul_f32 v[70:71], v[76:77], v[30:31] op_sel_hi:[1,0]
	v_pk_mul_f32 v[72:73], v[76:77], v[30:31] op_sel:[0,1]
	v_pk_fma_f32 v[66:67], v[32:33], v[24:25], v[66:67] op_sel_hi:[1,0,1]
	v_pk_fma_f32 v[68:69], v[32:33], v[24:25], v[68:69] op_sel:[0,1,0]
	v_pk_fma_f32 v[70:71], v[32:33], v[26:27], v[70:71] op_sel_hi:[1,0,1]
	v_pk_fma_f32 v[72:73], v[32:33], v[26:27], v[72:73] op_sel:[0,1,0]
	v_pk_fma_f32 v[0:1], v[0:1], v[20:21], v[66:67] op_sel_hi:[1,0,1]
	v_pk_fma_f32 v[2:3], v[2:3], v[20:21], v[68:69] op_sel:[0,1,0]
	v_pk_fma_f32 v[4:5], v[4:5], v[22:23], v[70:71] op_sel_hi:[1,0,1]
	v_pk_fma_f32 v[6:7], v[6:7], v[22:23], v[72:73] op_sel:[0,1,0]
	ds_write_b32 v84, v36 offset:2304
	ds_write_b32 v84, v76 offset:14592
	s_waitcnt lgkmcnt(7)
	v_pk_mul_f32 v[8:9], v[0:1], v[40:41] op_sel_hi:[1,0]
	v_pk_mul_f32 v[10:11], v[0:1], v[44:45] op_sel_hi:[1,0]
	ds_read_b128 v[12:15], v80 offset:31488
	v_pk_fma_f32 v[8:9], v[2:3], v[40:41], v[8:9] op_sel:[0,1,0]
	v_pk_fma_f32 v[10:11], v[2:3], v[44:45], v[10:11] op_sel:[0,1,0]
	ds_read_b128 v[16:19], v80 offset:30720
	v_pk_fma_f32 v[8:9], v[4:5], v[42:43], v[8:9] op_sel_hi:[1,0,1]
	v_pk_fma_f32 v[10:11], v[4:5], v[46:47], v[10:11] op_sel_hi:[1,0,1]
	ds_read_b128 v[20:23], v80 offset:30976
	v_pk_fma_f32 v[8:9], v[6:7], v[42:43], v[8:9] op_sel:[0,1,0]
	v_pk_fma_f32 v[10:11], v[6:7], v[46:47], v[10:11] op_sel:[0,1,0]
	ds_read_b128 v[24:27], v80 offset:31232
	v_add_f32_dpp v74, v9, v8 row_ror:8 row_mask:0xf bank_mask:0xf bound_ctrl:1
	v_add_f32_dpp v75, v11, v10 row_ror:8 row_mask:0xf bank_mask:0xf bound_ctrl:1
	ds_read_b128 v[28:31], v80 offset:31744
	v_add_f32_dpp v74, v74, v74 quad_perm:[1,0,3,2] row_mask:0xf bank_mask:0xf bound_ctrl:1
	v_add_f32_dpp v75, v75, v75 quad_perm:[1,0,3,2] row_mask:0xf bank_mask:0xf bound_ctrl:1
	ds_read_b32 v32, v81 offset:32000
	v_add_f32_dpp v74, v74, v74 quad_perm:[2,3,0,1] row_mask:0xf bank_mask:0xf bound_ctrl:1
	v_add_f32_dpp v75, v75, v75 quad_perm:[2,3,0,1] row_mask:0xf bank_mask:0xf bound_ctrl:1
	ds_read_b32 v33, v82 offset:32000
	v_add_f32_dpp v76, v74, v74 row_half_mirror row_mask:0xf bank_mask:0xf bound_ctrl:1
	v_add_f32_dpp v64, v75, v75 row_half_mirror row_mask:0xf bank_mask:0xf bound_ctrl:1
	s_nop 0
	v_mov_b32_dpp v77, v76 row_ror:8 row_mask:0xf bank_mask:0xf bound_ctrl:1
	s_waitcnt lgkmcnt(9)
	v_pk_mul_f32 v[66:67], v[76:77], v[56:57] op_sel_hi:[1,0]
	v_pk_mul_f32 v[68:69], v[76:77], v[56:57] op_sel:[0,1]
	v_pk_mul_f32 v[70:71], v[76:77], v[58:59] op_sel_hi:[1,0]
	v_pk_mul_f32 v[72:73], v[76:77], v[58:59] op_sel:[0,1]
	v_pk_fma_f32 v[66:67], v[60:61], v[52:53], v[66:67] op_sel_hi:[1,0,1]
	v_pk_fma_f32 v[68:69], v[60:61], v[52:53], v[68:69] op_sel:[0,1,0]
	v_pk_fma_f32 v[70:71], v[60:61], v[54:55], v[70:71] op_sel_hi:[1,0,1]
	v_pk_fma_f32 v[72:73], v[60:61], v[54:55], v[72:73] op_sel:[0,1,0]
	v_pk_fma_f32 v[0:1], v[0:1], v[48:49], v[66:67] op_sel_hi:[1,0,1]
	v_pk_fma_f32 v[2:3], v[2:3], v[48:49], v[68:69] op_sel:[0,1,0]
	v_pk_fma_f32 v[4:5], v[4:5], v[50:51], v[70:71] op_sel_hi:[1,0,1]
	v_pk_fma_f32 v[6:7], v[6:7], v[50:51], v[72:73] op_sel:[0,1,0]
	ds_write_b32 v84, v64 offset:2432
	ds_write_b32 v84, v76 offset:14720
	s_waitcnt lgkmcnt(7)
	v_pk_mul_f32 v[8:9], v[0:1], v[12:13] op_sel_hi:[1,0]
	v_pk_mul_f32 v[10:11], v[0:1], v[16:17] op_sel_hi:[1,0]
	ds_read_b128 v[40:43], v80 offset:33024
	v_pk_fma_f32 v[8:9], v[2:3], v[12:13], v[8:9] op_sel:[0,1,0]
	v_pk_fma_f32 v[10:11], v[2:3], v[16:17], v[10:11] op_sel:[0,1,0]
	ds_read_b128 v[44:47], v80 offset:32256
	v_pk_fma_f32 v[8:9], v[4:5], v[14:15], v[8:9] op_sel_hi:[1,0,1]
	v_pk_fma_f32 v[10:11], v[4:5], v[18:19], v[10:11] op_sel_hi:[1,0,1]
	ds_read_b128 v[48:51], v80 offset:32512
	v_pk_fma_f32 v[8:9], v[6:7], v[14:15], v[8:9] op_sel:[0,1,0]
	v_pk_fma_f32 v[10:11], v[6:7], v[18:19], v[10:11] op_sel:[0,1,0]
	ds_read_b128 v[52:55], v80 offset:32768
	v_add_f32_dpp v74, v9, v8 row_ror:8 row_mask:0xf bank_mask:0xf bound_ctrl:1
	v_add_f32_dpp v75, v11, v10 row_ror:8 row_mask:0xf bank_mask:0xf bound_ctrl:1
	ds_read_b128 v[56:59], v80 offset:33280
	v_add_f32_dpp v74, v74, v74 quad_perm:[1,0,3,2] row_mask:0xf bank_mask:0xf bound_ctrl:1
	v_add_f32_dpp v75, v75, v75 quad_perm:[1,0,3,2] row_mask:0xf bank_mask:0xf bound_ctrl:1
	ds_read_b32 v60, v81 offset:33536
	v_add_f32_dpp v74, v74, v74 quad_perm:[2,3,0,1] row_mask:0xf bank_mask:0xf bound_ctrl:1
	v_add_f32_dpp v75, v75, v75 quad_perm:[2,3,0,1] row_mask:0xf bank_mask:0xf bound_ctrl:1
	ds_read_b32 v61, v82 offset:33536
	v_add_f32_dpp v76, v74, v74 row_half_mirror row_mask:0xf bank_mask:0xf bound_ctrl:1
	v_add_f32_dpp v36, v75, v75 row_half_mirror row_mask:0xf bank_mask:0xf bound_ctrl:1
	s_nop 0
	v_mov_b32_dpp v77, v76 row_ror:8 row_mask:0xf bank_mask:0xf bound_ctrl:1
	s_waitcnt lgkmcnt(9)
	v_pk_mul_f32 v[66:67], v[76:77], v[28:29] op_sel_hi:[1,0]
	v_pk_mul_f32 v[68:69], v[76:77], v[28:29] op_sel:[0,1]
	v_pk_mul_f32 v[70:71], v[76:77], v[30:31] op_sel_hi:[1,0]
	v_pk_mul_f32 v[72:73], v[76:77], v[30:31] op_sel:[0,1]
	v_pk_fma_f32 v[66:67], v[32:33], v[24:25], v[66:67] op_sel_hi:[1,0,1]
	v_pk_fma_f32 v[68:69], v[32:33], v[24:25], v[68:69] op_sel:[0,1,0]
	v_pk_fma_f32 v[70:71], v[32:33], v[26:27], v[70:71] op_sel_hi:[1,0,1]
	v_pk_fma_f32 v[72:73], v[32:33], v[26:27], v[72:73] op_sel:[0,1,0]
	v_pk_fma_f32 v[0:1], v[0:1], v[20:21], v[66:67] op_sel_hi:[1,0,1]
	v_pk_fma_f32 v[2:3], v[2:3], v[20:21], v[68:69] op_sel:[0,1,0]
	v_pk_fma_f32 v[4:5], v[4:5], v[22:23], v[70:71] op_sel_hi:[1,0,1]
	v_pk_fma_f32 v[6:7], v[6:7], v[22:23], v[72:73] op_sel:[0,1,0]
	ds_write_b32 v84, v36 offset:2560
	ds_write_b32 v84, v76 offset:14848
	s_waitcnt lgkmcnt(7)
	v_pk_mul_f32 v[8:9], v[0:1], v[40:41] op_sel_hi:[1,0]
	v_pk_mul_f32 v[10:11], v[0:1], v[44:45] op_sel_hi:[1,0]
	ds_read_b128 v[12:15], v80 offset:34560
	v_pk_fma_f32 v[8:9], v[2:3], v[40:41], v[8:9] op_sel:[0,1,0]
	v_pk_fma_f32 v[10:11], v[2:3], v[44:45], v[10:11] op_sel:[0,1,0]
	ds_read_b128 v[16:19], v80 offset:33792
	v_pk_fma_f32 v[8:9], v[4:5], v[42:43], v[8:9] op_sel_hi:[1,0,1]
	v_pk_fma_f32 v[10:11], v[4:5], v[46:47], v[10:11] op_sel_hi:[1,0,1]
	ds_read_b128 v[20:23], v80 offset:34048
	v_pk_fma_f32 v[8:9], v[6:7], v[42:43], v[8:9] op_sel:[0,1,0]
	v_pk_fma_f32 v[10:11], v[6:7], v[46:47], v[10:11] op_sel:[0,1,0]
	ds_read_b128 v[24:27], v80 offset:34304
	v_add_f32_dpp v74, v9, v8 row_ror:8 row_mask:0xf bank_mask:0xf bound_ctrl:1
	v_add_f32_dpp v75, v11, v10 row_ror:8 row_mask:0xf bank_mask:0xf bound_ctrl:1
	ds_read_b128 v[28:31], v80 offset:34816
	v_add_f32_dpp v74, v74, v74 quad_perm:[1,0,3,2] row_mask:0xf bank_mask:0xf bound_ctrl:1
	v_add_f32_dpp v75, v75, v75 quad_perm:[1,0,3,2] row_mask:0xf bank_mask:0xf bound_ctrl:1
	ds_read_b32 v32, v81 offset:35072
	v_add_f32_dpp v74, v74, v74 quad_perm:[2,3,0,1] row_mask:0xf bank_mask:0xf bound_ctrl:1
	v_add_f32_dpp v75, v75, v75 quad_perm:[2,3,0,1] row_mask:0xf bank_mask:0xf bound_ctrl:1
	ds_read_b32 v33, v82 offset:35072
	v_add_f32_dpp v76, v74, v74 row_half_mirror row_mask:0xf bank_mask:0xf bound_ctrl:1
	v_add_f32_dpp v64, v75, v75 row_half_mirror row_mask:0xf bank_mask:0xf bound_ctrl:1
	s_nop 0
	v_mov_b32_dpp v77, v76 row_ror:8 row_mask:0xf bank_mask:0xf bound_ctrl:1
	s_waitcnt lgkmcnt(9)
	v_pk_mul_f32 v[66:67], v[76:77], v[56:57] op_sel_hi:[1,0]
	v_pk_mul_f32 v[68:69], v[76:77], v[56:57] op_sel:[0,1]
	v_pk_mul_f32 v[70:71], v[76:77], v[58:59] op_sel_hi:[1,0]
	v_pk_mul_f32 v[72:73], v[76:77], v[58:59] op_sel:[0,1]
	v_pk_fma_f32 v[66:67], v[60:61], v[52:53], v[66:67] op_sel_hi:[1,0,1]
	v_pk_fma_f32 v[68:69], v[60:61], v[52:53], v[68:69] op_sel:[0,1,0]
	v_pk_fma_f32 v[70:71], v[60:61], v[54:55], v[70:71] op_sel_hi:[1,0,1]
	v_pk_fma_f32 v[72:73], v[60:61], v[54:55], v[72:73] op_sel:[0,1,0]
	v_pk_fma_f32 v[0:1], v[0:1], v[48:49], v[66:67] op_sel_hi:[1,0,1]
	v_pk_fma_f32 v[2:3], v[2:3], v[48:49], v[68:69] op_sel:[0,1,0]
	v_pk_fma_f32 v[4:5], v[4:5], v[50:51], v[70:71] op_sel_hi:[1,0,1]
	v_pk_fma_f32 v[6:7], v[6:7], v[50:51], v[72:73] op_sel:[0,1,0]
	ds_write_b32 v84, v64 offset:2688
	ds_write_b32 v84, v76 offset:14976
	s_waitcnt lgkmcnt(7)
	v_pk_mul_f32 v[8:9], v[0:1], v[12:13] op_sel_hi:[1,0]
	v_pk_mul_f32 v[10:11], v[0:1], v[16:17] op_sel_hi:[1,0]
	ds_read_b128 v[40:43], v80 offset:36096
	v_pk_fma_f32 v[8:9], v[2:3], v[12:13], v[8:9] op_sel:[0,1,0]
	v_pk_fma_f32 v[10:11], v[2:3], v[16:17], v[10:11] op_sel:[0,1,0]
	ds_read_b128 v[44:47], v80 offset:35328
	v_pk_fma_f32 v[8:9], v[4:5], v[14:15], v[8:9] op_sel_hi:[1,0,1]
	v_pk_fma_f32 v[10:11], v[4:5], v[18:19], v[10:11] op_sel_hi:[1,0,1]
	ds_read_b128 v[48:51], v80 offset:35584
	v_pk_fma_f32 v[8:9], v[6:7], v[14:15], v[8:9] op_sel:[0,1,0]
	v_pk_fma_f32 v[10:11], v[6:7], v[18:19], v[10:11] op_sel:[0,1,0]
	ds_read_b128 v[52:55], v80 offset:35840
	v_add_f32_dpp v74, v9, v8 row_ror:8 row_mask:0xf bank_mask:0xf bound_ctrl:1
	v_add_f32_dpp v75, v11, v10 row_ror:8 row_mask:0xf bank_mask:0xf bound_ctrl:1
	ds_read_b128 v[56:59], v80 offset:36352
	v_add_f32_dpp v74, v74, v74 quad_perm:[1,0,3,2] row_mask:0xf bank_mask:0xf bound_ctrl:1
	v_add_f32_dpp v75, v75, v75 quad_perm:[1,0,3,2] row_mask:0xf bank_mask:0xf bound_ctrl:1
	ds_read_b32 v60, v81 offset:36608
	v_add_f32_dpp v74, v74, v74 quad_perm:[2,3,0,1] row_mask:0xf bank_mask:0xf bound_ctrl:1
	v_add_f32_dpp v75, v75, v75 quad_perm:[2,3,0,1] row_mask:0xf bank_mask:0xf bound_ctrl:1
	ds_read_b32 v61, v82 offset:36608
	v_add_f32_dpp v76, v74, v74 row_half_mirror row_mask:0xf bank_mask:0xf bound_ctrl:1
	v_add_f32_dpp v36, v75, v75 row_half_mirror row_mask:0xf bank_mask:0xf bound_ctrl:1
	s_nop 0
	v_mov_b32_dpp v77, v76 row_ror:8 row_mask:0xf bank_mask:0xf bound_ctrl:1
	s_waitcnt lgkmcnt(9)
	v_pk_mul_f32 v[66:67], v[76:77], v[28:29] op_sel_hi:[1,0]
	v_pk_mul_f32 v[68:69], v[76:77], v[28:29] op_sel:[0,1]
	v_pk_mul_f32 v[70:71], v[76:77], v[30:31] op_sel_hi:[1,0]
	v_pk_mul_f32 v[72:73], v[76:77], v[30:31] op_sel:[0,1]
	v_pk_fma_f32 v[66:67], v[32:33], v[24:25], v[66:67] op_sel_hi:[1,0,1]
	v_pk_fma_f32 v[68:69], v[32:33], v[24:25], v[68:69] op_sel:[0,1,0]
	v_pk_fma_f32 v[70:71], v[32:33], v[26:27], v[70:71] op_sel_hi:[1,0,1]
	v_pk_fma_f32 v[72:73], v[32:33], v[26:27], v[72:73] op_sel:[0,1,0]
	v_pk_fma_f32 v[0:1], v[0:1], v[20:21], v[66:67] op_sel_hi:[1,0,1]
	v_pk_fma_f32 v[2:3], v[2:3], v[20:21], v[68:69] op_sel:[0,1,0]
	v_pk_fma_f32 v[4:5], v[4:5], v[22:23], v[70:71] op_sel_hi:[1,0,1]
	v_pk_fma_f32 v[6:7], v[6:7], v[22:23], v[72:73] op_sel:[0,1,0]
	ds_write_b32 v84, v36 offset:2816
	ds_write_b32 v84, v76 offset:15104
	s_waitcnt lgkmcnt(7)
	v_pk_mul_f32 v[8:9], v[0:1], v[40:41] op_sel_hi:[1,0]
	v_pk_mul_f32 v[10:11], v[0:1], v[44:45] op_sel_hi:[1,0]
	ds_read_b128 v[12:15], v80 offset:37632
	v_pk_fma_f32 v[8:9], v[2:3], v[40:41], v[8:9] op_sel:[0,1,0]
	v_pk_fma_f32 v[10:11], v[2:3], v[44:45], v[10:11] op_sel:[0,1,0]
	ds_read_b128 v[16:19], v80 offset:36864
	v_pk_fma_f32 v[8:9], v[4:5], v[42:43], v[8:9] op_sel_hi:[1,0,1]
	v_pk_fma_f32 v[10:11], v[4:5], v[46:47], v[10:11] op_sel_hi:[1,0,1]
	ds_read_b128 v[20:23], v80 offset:37120
	v_pk_fma_f32 v[8:9], v[6:7], v[42:43], v[8:9] op_sel:[0,1,0]
	v_pk_fma_f32 v[10:11], v[6:7], v[46:47], v[10:11] op_sel:[0,1,0]
	ds_read_b128 v[24:27], v80 offset:37376
	v_add_f32_dpp v74, v9, v8 row_ror:8 row_mask:0xf bank_mask:0xf bound_ctrl:1
	v_add_f32_dpp v75, v11, v10 row_ror:8 row_mask:0xf bank_mask:0xf bound_ctrl:1
	ds_read_b128 v[28:31], v80 offset:37888
	v_add_f32_dpp v74, v74, v74 quad_perm:[1,0,3,2] row_mask:0xf bank_mask:0xf bound_ctrl:1
	v_add_f32_dpp v75, v75, v75 quad_perm:[1,0,3,2] row_mask:0xf bank_mask:0xf bound_ctrl:1
	ds_read_b32 v32, v81 offset:38144
	v_add_f32_dpp v74, v74, v74 quad_perm:[2,3,0,1] row_mask:0xf bank_mask:0xf bound_ctrl:1
	v_add_f32_dpp v75, v75, v75 quad_perm:[2,3,0,1] row_mask:0xf bank_mask:0xf bound_ctrl:1
	ds_read_b32 v33, v82 offset:38144
	v_add_f32_dpp v76, v74, v74 row_half_mirror row_mask:0xf bank_mask:0xf bound_ctrl:1
	v_add_f32_dpp v64, v75, v75 row_half_mirror row_mask:0xf bank_mask:0xf bound_ctrl:1
	s_nop 0
	v_mov_b32_dpp v77, v76 row_ror:8 row_mask:0xf bank_mask:0xf bound_ctrl:1
	s_waitcnt lgkmcnt(9)
	v_pk_mul_f32 v[66:67], v[76:77], v[56:57] op_sel_hi:[1,0]
	v_pk_mul_f32 v[68:69], v[76:77], v[56:57] op_sel:[0,1]
	v_pk_mul_f32 v[70:71], v[76:77], v[58:59] op_sel_hi:[1,0]
	v_pk_mul_f32 v[72:73], v[76:77], v[58:59] op_sel:[0,1]
	v_pk_fma_f32 v[66:67], v[60:61], v[52:53], v[66:67] op_sel_hi:[1,0,1]
	v_pk_fma_f32 v[68:69], v[60:61], v[52:53], v[68:69] op_sel:[0,1,0]
	v_pk_fma_f32 v[70:71], v[60:61], v[54:55], v[70:71] op_sel_hi:[1,0,1]
	v_pk_fma_f32 v[72:73], v[60:61], v[54:55], v[72:73] op_sel:[0,1,0]
	v_pk_fma_f32 v[0:1], v[0:1], v[48:49], v[66:67] op_sel_hi:[1,0,1]
	v_pk_fma_f32 v[2:3], v[2:3], v[48:49], v[68:69] op_sel:[0,1,0]
	v_pk_fma_f32 v[4:5], v[4:5], v[50:51], v[70:71] op_sel_hi:[1,0,1]
	v_pk_fma_f32 v[6:7], v[6:7], v[50:51], v[72:73] op_sel:[0,1,0]
	ds_write_b32 v84, v64 offset:2944
	ds_write_b32 v84, v76 offset:15232
	s_waitcnt lgkmcnt(7)
	v_pk_mul_f32 v[8:9], v[0:1], v[12:13] op_sel_hi:[1,0]
	v_pk_mul_f32 v[10:11], v[0:1], v[16:17] op_sel_hi:[1,0]
	ds_read_b128 v[40:43], v80 offset:39168
	v_pk_fma_f32 v[8:9], v[2:3], v[12:13], v[8:9] op_sel:[0,1,0]
	v_pk_fma_f32 v[10:11], v[2:3], v[16:17], v[10:11] op_sel:[0,1,0]
	ds_read_b128 v[44:47], v80 offset:38400
	v_pk_fma_f32 v[8:9], v[4:5], v[14:15], v[8:9] op_sel_hi:[1,0,1]
	v_pk_fma_f32 v[10:11], v[4:5], v[18:19], v[10:11] op_sel_hi:[1,0,1]
	ds_read_b128 v[48:51], v80 offset:38656
	v_pk_fma_f32 v[8:9], v[6:7], v[14:15], v[8:9] op_sel:[0,1,0]
	v_pk_fma_f32 v[10:11], v[6:7], v[18:19], v[10:11] op_sel:[0,1,0]
	ds_read_b128 v[52:55], v80 offset:38912
	v_add_f32_dpp v74, v9, v8 row_ror:8 row_mask:0xf bank_mask:0xf bound_ctrl:1
	v_add_f32_dpp v75, v11, v10 row_ror:8 row_mask:0xf bank_mask:0xf bound_ctrl:1
	ds_read_b128 v[56:59], v80 offset:39424
	v_add_f32_dpp v74, v74, v74 quad_perm:[1,0,3,2] row_mask:0xf bank_mask:0xf bound_ctrl:1
	v_add_f32_dpp v75, v75, v75 quad_perm:[1,0,3,2] row_mask:0xf bank_mask:0xf bound_ctrl:1
	ds_read_b32 v60, v81 offset:39680
	v_add_f32_dpp v74, v74, v74 quad_perm:[2,3,0,1] row_mask:0xf bank_mask:0xf bound_ctrl:1
	v_add_f32_dpp v75, v75, v75 quad_perm:[2,3,0,1] row_mask:0xf bank_mask:0xf bound_ctrl:1
	ds_read_b32 v61, v82 offset:39680
	v_add_f32_dpp v76, v74, v74 row_half_mirror row_mask:0xf bank_mask:0xf bound_ctrl:1
	v_add_f32_dpp v36, v75, v75 row_half_mirror row_mask:0xf bank_mask:0xf bound_ctrl:1
	s_nop 0
	v_mov_b32_dpp v77, v76 row_ror:8 row_mask:0xf bank_mask:0xf bound_ctrl:1
	s_waitcnt lgkmcnt(9)
	v_pk_mul_f32 v[66:67], v[76:77], v[28:29] op_sel_hi:[1,0]
	v_pk_mul_f32 v[68:69], v[76:77], v[28:29] op_sel:[0,1]
	v_pk_mul_f32 v[70:71], v[76:77], v[30:31] op_sel_hi:[1,0]
	v_pk_mul_f32 v[72:73], v[76:77], v[30:31] op_sel:[0,1]
	v_pk_fma_f32 v[66:67], v[32:33], v[24:25], v[66:67] op_sel_hi:[1,0,1]
	v_pk_fma_f32 v[68:69], v[32:33], v[24:25], v[68:69] op_sel:[0,1,0]
	v_pk_fma_f32 v[70:71], v[32:33], v[26:27], v[70:71] op_sel_hi:[1,0,1]
	v_pk_fma_f32 v[72:73], v[32:33], v[26:27], v[72:73] op_sel:[0,1,0]
	v_pk_fma_f32 v[0:1], v[0:1], v[20:21], v[66:67] op_sel_hi:[1,0,1]
	v_pk_fma_f32 v[2:3], v[2:3], v[20:21], v[68:69] op_sel:[0,1,0]
	v_pk_fma_f32 v[4:5], v[4:5], v[22:23], v[70:71] op_sel_hi:[1,0,1]
	v_pk_fma_f32 v[6:7], v[6:7], v[22:23], v[72:73] op_sel:[0,1,0]
	ds_write_b32 v84, v36 offset:3072
	ds_write_b32 v84, v76 offset:15360
	s_waitcnt lgkmcnt(7)
	v_pk_mul_f32 v[8:9], v[0:1], v[40:41] op_sel_hi:[1,0]
	v_pk_mul_f32 v[10:11], v[0:1], v[44:45] op_sel_hi:[1,0]
	ds_read_b128 v[12:15], v80 offset:40704
	v_pk_fma_f32 v[8:9], v[2:3], v[40:41], v[8:9] op_sel:[0,1,0]
	v_pk_fma_f32 v[10:11], v[2:3], v[44:45], v[10:11] op_sel:[0,1,0]
	ds_read_b128 v[16:19], v80 offset:39936
	v_pk_fma_f32 v[8:9], v[4:5], v[42:43], v[8:9] op_sel_hi:[1,0,1]
	v_pk_fma_f32 v[10:11], v[4:5], v[46:47], v[10:11] op_sel_hi:[1,0,1]
	ds_read_b128 v[20:23], v80 offset:40192
	v_pk_fma_f32 v[8:9], v[6:7], v[42:43], v[8:9] op_sel:[0,1,0]
	v_pk_fma_f32 v[10:11], v[6:7], v[46:47], v[10:11] op_sel:[0,1,0]
	ds_read_b128 v[24:27], v80 offset:40448
	v_add_f32_dpp v74, v9, v8 row_ror:8 row_mask:0xf bank_mask:0xf bound_ctrl:1
	v_add_f32_dpp v75, v11, v10 row_ror:8 row_mask:0xf bank_mask:0xf bound_ctrl:1
	ds_read_b128 v[28:31], v80 offset:40960
	v_add_f32_dpp v74, v74, v74 quad_perm:[1,0,3,2] row_mask:0xf bank_mask:0xf bound_ctrl:1
	v_add_f32_dpp v75, v75, v75 quad_perm:[1,0,3,2] row_mask:0xf bank_mask:0xf bound_ctrl:1
	ds_read_b32 v32, v81 offset:41216
	v_add_f32_dpp v74, v74, v74 quad_perm:[2,3,0,1] row_mask:0xf bank_mask:0xf bound_ctrl:1
	v_add_f32_dpp v75, v75, v75 quad_perm:[2,3,0,1] row_mask:0xf bank_mask:0xf bound_ctrl:1
	ds_read_b32 v33, v82 offset:41216
	v_add_f32_dpp v76, v74, v74 row_half_mirror row_mask:0xf bank_mask:0xf bound_ctrl:1
	v_add_f32_dpp v64, v75, v75 row_half_mirror row_mask:0xf bank_mask:0xf bound_ctrl:1
	s_nop 0
	v_mov_b32_dpp v77, v76 row_ror:8 row_mask:0xf bank_mask:0xf bound_ctrl:1
	s_waitcnt lgkmcnt(9)
	v_pk_mul_f32 v[66:67], v[76:77], v[56:57] op_sel_hi:[1,0]
	v_pk_mul_f32 v[68:69], v[76:77], v[56:57] op_sel:[0,1]
	v_pk_mul_f32 v[70:71], v[76:77], v[58:59] op_sel_hi:[1,0]
	v_pk_mul_f32 v[72:73], v[76:77], v[58:59] op_sel:[0,1]
	v_pk_fma_f32 v[66:67], v[60:61], v[52:53], v[66:67] op_sel_hi:[1,0,1]
	v_pk_fma_f32 v[68:69], v[60:61], v[52:53], v[68:69] op_sel:[0,1,0]
	v_pk_fma_f32 v[70:71], v[60:61], v[54:55], v[70:71] op_sel_hi:[1,0,1]
	v_pk_fma_f32 v[72:73], v[60:61], v[54:55], v[72:73] op_sel:[0,1,0]
	v_pk_fma_f32 v[0:1], v[0:1], v[48:49], v[66:67] op_sel_hi:[1,0,1]
	v_pk_fma_f32 v[2:3], v[2:3], v[48:49], v[68:69] op_sel:[0,1,0]
	v_pk_fma_f32 v[4:5], v[4:5], v[50:51], v[70:71] op_sel_hi:[1,0,1]
	v_pk_fma_f32 v[6:7], v[6:7], v[50:51], v[72:73] op_sel:[0,1,0]
	ds_write_b32 v84, v64 offset:3200
	ds_write_b32 v84, v76 offset:15488
	s_waitcnt lgkmcnt(7)
	v_pk_mul_f32 v[8:9], v[0:1], v[12:13] op_sel_hi:[1,0]
	v_pk_mul_f32 v[10:11], v[0:1], v[16:17] op_sel_hi:[1,0]
	ds_read_b128 v[40:43], v80 offset:42240
	v_pk_fma_f32 v[8:9], v[2:3], v[12:13], v[8:9] op_sel:[0,1,0]
	v_pk_fma_f32 v[10:11], v[2:3], v[16:17], v[10:11] op_sel:[0,1,0]
	ds_read_b128 v[44:47], v80 offset:41472
	v_pk_fma_f32 v[8:9], v[4:5], v[14:15], v[8:9] op_sel_hi:[1,0,1]
	v_pk_fma_f32 v[10:11], v[4:5], v[18:19], v[10:11] op_sel_hi:[1,0,1]
	ds_read_b128 v[48:51], v80 offset:41728
	v_pk_fma_f32 v[8:9], v[6:7], v[14:15], v[8:9] op_sel:[0,1,0]
	v_pk_fma_f32 v[10:11], v[6:7], v[18:19], v[10:11] op_sel:[0,1,0]
	ds_read_b128 v[52:55], v80 offset:41984
	v_add_f32_dpp v74, v9, v8 row_ror:8 row_mask:0xf bank_mask:0xf bound_ctrl:1
	v_add_f32_dpp v75, v11, v10 row_ror:8 row_mask:0xf bank_mask:0xf bound_ctrl:1
	ds_read_b128 v[56:59], v80 offset:42496
	v_add_f32_dpp v74, v74, v74 quad_perm:[1,0,3,2] row_mask:0xf bank_mask:0xf bound_ctrl:1
	v_add_f32_dpp v75, v75, v75 quad_perm:[1,0,3,2] row_mask:0xf bank_mask:0xf bound_ctrl:1
	ds_read_b32 v60, v81 offset:42752
	v_add_f32_dpp v74, v74, v74 quad_perm:[2,3,0,1] row_mask:0xf bank_mask:0xf bound_ctrl:1
	v_add_f32_dpp v75, v75, v75 quad_perm:[2,3,0,1] row_mask:0xf bank_mask:0xf bound_ctrl:1
	ds_read_b32 v61, v82 offset:42752
	v_add_f32_dpp v76, v74, v74 row_half_mirror row_mask:0xf bank_mask:0xf bound_ctrl:1
	v_add_f32_dpp v36, v75, v75 row_half_mirror row_mask:0xf bank_mask:0xf bound_ctrl:1
	s_nop 0
	v_mov_b32_dpp v77, v76 row_ror:8 row_mask:0xf bank_mask:0xf bound_ctrl:1
	s_waitcnt lgkmcnt(9)
	v_pk_mul_f32 v[66:67], v[76:77], v[28:29] op_sel_hi:[1,0]
	v_pk_mul_f32 v[68:69], v[76:77], v[28:29] op_sel:[0,1]
	v_pk_mul_f32 v[70:71], v[76:77], v[30:31] op_sel_hi:[1,0]
	v_pk_mul_f32 v[72:73], v[76:77], v[30:31] op_sel:[0,1]
	v_pk_fma_f32 v[66:67], v[32:33], v[24:25], v[66:67] op_sel_hi:[1,0,1]
	v_pk_fma_f32 v[68:69], v[32:33], v[24:25], v[68:69] op_sel:[0,1,0]
	v_pk_fma_f32 v[70:71], v[32:33], v[26:27], v[70:71] op_sel_hi:[1,0,1]
	v_pk_fma_f32 v[72:73], v[32:33], v[26:27], v[72:73] op_sel:[0,1,0]
	v_pk_fma_f32 v[0:1], v[0:1], v[20:21], v[66:67] op_sel_hi:[1,0,1]
	v_pk_fma_f32 v[2:3], v[2:3], v[20:21], v[68:69] op_sel:[0,1,0]
	v_pk_fma_f32 v[4:5], v[4:5], v[22:23], v[70:71] op_sel_hi:[1,0,1]
	v_pk_fma_f32 v[6:7], v[6:7], v[22:23], v[72:73] op_sel:[0,1,0]
	ds_write_b32 v84, v36 offset:3328
	ds_write_b32 v84, v76 offset:15616
	s_waitcnt lgkmcnt(7)
	v_pk_mul_f32 v[8:9], v[0:1], v[40:41] op_sel_hi:[1,0]
	v_pk_mul_f32 v[10:11], v[0:1], v[44:45] op_sel_hi:[1,0]
	ds_read_b128 v[12:15], v80 offset:43776
	v_pk_fma_f32 v[8:9], v[2:3], v[40:41], v[8:9] op_sel:[0,1,0]
	v_pk_fma_f32 v[10:11], v[2:3], v[44:45], v[10:11] op_sel:[0,1,0]
	ds_read_b128 v[16:19], v80 offset:43008
	v_pk_fma_f32 v[8:9], v[4:5], v[42:43], v[8:9] op_sel_hi:[1,0,1]
	v_pk_fma_f32 v[10:11], v[4:5], v[46:47], v[10:11] op_sel_hi:[1,0,1]
	ds_read_b128 v[20:23], v80 offset:43264
	v_pk_fma_f32 v[8:9], v[6:7], v[42:43], v[8:9] op_sel:[0,1,0]
	v_pk_fma_f32 v[10:11], v[6:7], v[46:47], v[10:11] op_sel:[0,1,0]
	ds_read_b128 v[24:27], v80 offset:43520
	v_add_f32_dpp v74, v9, v8 row_ror:8 row_mask:0xf bank_mask:0xf bound_ctrl:1
	v_add_f32_dpp v75, v11, v10 row_ror:8 row_mask:0xf bank_mask:0xf bound_ctrl:1
	ds_read_b128 v[28:31], v80 offset:44032
	v_add_f32_dpp v74, v74, v74 quad_perm:[1,0,3,2] row_mask:0xf bank_mask:0xf bound_ctrl:1
	v_add_f32_dpp v75, v75, v75 quad_perm:[1,0,3,2] row_mask:0xf bank_mask:0xf bound_ctrl:1
	ds_read_b32 v32, v81 offset:44288
	v_add_f32_dpp v74, v74, v74 quad_perm:[2,3,0,1] row_mask:0xf bank_mask:0xf bound_ctrl:1
	v_add_f32_dpp v75, v75, v75 quad_perm:[2,3,0,1] row_mask:0xf bank_mask:0xf bound_ctrl:1
	ds_read_b32 v33, v82 offset:44288
	v_add_f32_dpp v76, v74, v74 row_half_mirror row_mask:0xf bank_mask:0xf bound_ctrl:1
	v_add_f32_dpp v64, v75, v75 row_half_mirror row_mask:0xf bank_mask:0xf bound_ctrl:1
	s_nop 0
	v_mov_b32_dpp v77, v76 row_ror:8 row_mask:0xf bank_mask:0xf bound_ctrl:1
	s_waitcnt lgkmcnt(9)
	v_pk_mul_f32 v[66:67], v[76:77], v[56:57] op_sel_hi:[1,0]
	v_pk_mul_f32 v[68:69], v[76:77], v[56:57] op_sel:[0,1]
	v_pk_mul_f32 v[70:71], v[76:77], v[58:59] op_sel_hi:[1,0]
	v_pk_mul_f32 v[72:73], v[76:77], v[58:59] op_sel:[0,1]
	v_pk_fma_f32 v[66:67], v[60:61], v[52:53], v[66:67] op_sel_hi:[1,0,1]
	v_pk_fma_f32 v[68:69], v[60:61], v[52:53], v[68:69] op_sel:[0,1,0]
	v_pk_fma_f32 v[70:71], v[60:61], v[54:55], v[70:71] op_sel_hi:[1,0,1]
	v_pk_fma_f32 v[72:73], v[60:61], v[54:55], v[72:73] op_sel:[0,1,0]
	v_pk_fma_f32 v[0:1], v[0:1], v[48:49], v[66:67] op_sel_hi:[1,0,1]
	v_pk_fma_f32 v[2:3], v[2:3], v[48:49], v[68:69] op_sel:[0,1,0]
	v_pk_fma_f32 v[4:5], v[4:5], v[50:51], v[70:71] op_sel_hi:[1,0,1]
	v_pk_fma_f32 v[6:7], v[6:7], v[50:51], v[72:73] op_sel:[0,1,0]
	ds_write_b32 v84, v64 offset:3456
	ds_write_b32 v84, v76 offset:15744
	s_waitcnt lgkmcnt(7)
	v_pk_mul_f32 v[8:9], v[0:1], v[12:13] op_sel_hi:[1,0]
	v_pk_mul_f32 v[10:11], v[0:1], v[16:17] op_sel_hi:[1,0]
	ds_read_b128 v[40:43], v80 offset:45312
	v_pk_fma_f32 v[8:9], v[2:3], v[12:13], v[8:9] op_sel:[0,1,0]
	v_pk_fma_f32 v[10:11], v[2:3], v[16:17], v[10:11] op_sel:[0,1,0]
	ds_read_b128 v[44:47], v80 offset:44544
	v_pk_fma_f32 v[8:9], v[4:5], v[14:15], v[8:9] op_sel_hi:[1,0,1]
	v_pk_fma_f32 v[10:11], v[4:5], v[18:19], v[10:11] op_sel_hi:[1,0,1]
	ds_read_b128 v[48:51], v80 offset:44800
	v_pk_fma_f32 v[8:9], v[6:7], v[14:15], v[8:9] op_sel:[0,1,0]
	v_pk_fma_f32 v[10:11], v[6:7], v[18:19], v[10:11] op_sel:[0,1,0]
	ds_read_b128 v[52:55], v80 offset:45056
	v_add_f32_dpp v74, v9, v8 row_ror:8 row_mask:0xf bank_mask:0xf bound_ctrl:1
	v_add_f32_dpp v75, v11, v10 row_ror:8 row_mask:0xf bank_mask:0xf bound_ctrl:1
	ds_read_b128 v[56:59], v80 offset:45568
	v_add_f32_dpp v74, v74, v74 quad_perm:[1,0,3,2] row_mask:0xf bank_mask:0xf bound_ctrl:1
	v_add_f32_dpp v75, v75, v75 quad_perm:[1,0,3,2] row_mask:0xf bank_mask:0xf bound_ctrl:1
	ds_read_b32 v60, v81 offset:45824
	v_add_f32_dpp v74, v74, v74 quad_perm:[2,3,0,1] row_mask:0xf bank_mask:0xf bound_ctrl:1
	v_add_f32_dpp v75, v75, v75 quad_perm:[2,3,0,1] row_mask:0xf bank_mask:0xf bound_ctrl:1
	ds_read_b32 v61, v82 offset:45824
	v_add_f32_dpp v76, v74, v74 row_half_mirror row_mask:0xf bank_mask:0xf bound_ctrl:1
	v_add_f32_dpp v36, v75, v75 row_half_mirror row_mask:0xf bank_mask:0xf bound_ctrl:1
	s_nop 0
	v_mov_b32_dpp v77, v76 row_ror:8 row_mask:0xf bank_mask:0xf bound_ctrl:1
	s_waitcnt lgkmcnt(9)
	v_pk_mul_f32 v[66:67], v[76:77], v[28:29] op_sel_hi:[1,0]
	v_pk_mul_f32 v[68:69], v[76:77], v[28:29] op_sel:[0,1]
	v_pk_mul_f32 v[70:71], v[76:77], v[30:31] op_sel_hi:[1,0]
	v_pk_mul_f32 v[72:73], v[76:77], v[30:31] op_sel:[0,1]
	v_pk_fma_f32 v[66:67], v[32:33], v[24:25], v[66:67] op_sel_hi:[1,0,1]
	v_pk_fma_f32 v[68:69], v[32:33], v[24:25], v[68:69] op_sel:[0,1,0]
	v_pk_fma_f32 v[70:71], v[32:33], v[26:27], v[70:71] op_sel_hi:[1,0,1]
	v_pk_fma_f32 v[72:73], v[32:33], v[26:27], v[72:73] op_sel:[0,1,0]
	v_pk_fma_f32 v[0:1], v[0:1], v[20:21], v[66:67] op_sel_hi:[1,0,1]
	v_pk_fma_f32 v[2:3], v[2:3], v[20:21], v[68:69] op_sel:[0,1,0]
	v_pk_fma_f32 v[4:5], v[4:5], v[22:23], v[70:71] op_sel_hi:[1,0,1]
	v_pk_fma_f32 v[6:7], v[6:7], v[22:23], v[72:73] op_sel:[0,1,0]
	ds_write_b32 v84, v36 offset:3584
	ds_write_b32 v84, v76 offset:15872
	s_waitcnt lgkmcnt(7)
	v_pk_mul_f32 v[8:9], v[0:1], v[40:41] op_sel_hi:[1,0]
	v_pk_mul_f32 v[10:11], v[0:1], v[44:45] op_sel_hi:[1,0]
	ds_read_b128 v[12:15], v80 offset:46848
	v_pk_fma_f32 v[8:9], v[2:3], v[40:41], v[8:9] op_sel:[0,1,0]
	v_pk_fma_f32 v[10:11], v[2:3], v[44:45], v[10:11] op_sel:[0,1,0]
	ds_read_b128 v[16:19], v80 offset:46080
	v_pk_fma_f32 v[8:9], v[4:5], v[42:43], v[8:9] op_sel_hi:[1,0,1]
	v_pk_fma_f32 v[10:11], v[4:5], v[46:47], v[10:11] op_sel_hi:[1,0,1]
	ds_read_b128 v[20:23], v80 offset:46336
	v_pk_fma_f32 v[8:9], v[6:7], v[42:43], v[8:9] op_sel:[0,1,0]
	v_pk_fma_f32 v[10:11], v[6:7], v[46:47], v[10:11] op_sel:[0,1,0]
	ds_read_b128 v[24:27], v80 offset:46592
	v_add_f32_dpp v74, v9, v8 row_ror:8 row_mask:0xf bank_mask:0xf bound_ctrl:1
	v_add_f32_dpp v75, v11, v10 row_ror:8 row_mask:0xf bank_mask:0xf bound_ctrl:1
	ds_read_b128 v[28:31], v80 offset:47104
	v_add_f32_dpp v74, v74, v74 quad_perm:[1,0,3,2] row_mask:0xf bank_mask:0xf bound_ctrl:1
	v_add_f32_dpp v75, v75, v75 quad_perm:[1,0,3,2] row_mask:0xf bank_mask:0xf bound_ctrl:1
	ds_read_b32 v32, v81 offset:47360
	v_add_f32_dpp v74, v74, v74 quad_perm:[2,3,0,1] row_mask:0xf bank_mask:0xf bound_ctrl:1
	v_add_f32_dpp v75, v75, v75 quad_perm:[2,3,0,1] row_mask:0xf bank_mask:0xf bound_ctrl:1
	ds_read_b32 v33, v82 offset:47360
	v_add_f32_dpp v76, v74, v74 row_half_mirror row_mask:0xf bank_mask:0xf bound_ctrl:1
	v_add_f32_dpp v64, v75, v75 row_half_mirror row_mask:0xf bank_mask:0xf bound_ctrl:1
	s_nop 0
	v_mov_b32_dpp v77, v76 row_ror:8 row_mask:0xf bank_mask:0xf bound_ctrl:1
	s_waitcnt lgkmcnt(9)
	v_pk_mul_f32 v[66:67], v[76:77], v[56:57] op_sel_hi:[1,0]
	v_pk_mul_f32 v[68:69], v[76:77], v[56:57] op_sel:[0,1]
	v_pk_mul_f32 v[70:71], v[76:77], v[58:59] op_sel_hi:[1,0]
	v_pk_mul_f32 v[72:73], v[76:77], v[58:59] op_sel:[0,1]
	v_pk_fma_f32 v[66:67], v[60:61], v[52:53], v[66:67] op_sel_hi:[1,0,1]
	v_pk_fma_f32 v[68:69], v[60:61], v[52:53], v[68:69] op_sel:[0,1,0]
	v_pk_fma_f32 v[70:71], v[60:61], v[54:55], v[70:71] op_sel_hi:[1,0,1]
	v_pk_fma_f32 v[72:73], v[60:61], v[54:55], v[72:73] op_sel:[0,1,0]
	v_pk_fma_f32 v[0:1], v[0:1], v[48:49], v[66:67] op_sel_hi:[1,0,1]
	v_pk_fma_f32 v[2:3], v[2:3], v[48:49], v[68:69] op_sel:[0,1,0]
	v_pk_fma_f32 v[4:5], v[4:5], v[50:51], v[70:71] op_sel_hi:[1,0,1]
	v_pk_fma_f32 v[6:7], v[6:7], v[50:51], v[72:73] op_sel:[0,1,0]
	ds_write_b32 v84, v64 offset:3712
	ds_write_b32 v84, v76 offset:16000
	s_waitcnt lgkmcnt(7)
	v_pk_mul_f32 v[8:9], v[0:1], v[12:13] op_sel_hi:[1,0]
	v_pk_mul_f32 v[10:11], v[0:1], v[16:17] op_sel_hi:[1,0]
	ds_read_b128 v[40:43], v80 offset:48384
	v_pk_fma_f32 v[8:9], v[2:3], v[12:13], v[8:9] op_sel:[0,1,0]
	v_pk_fma_f32 v[10:11], v[2:3], v[16:17], v[10:11] op_sel:[0,1,0]
	ds_read_b128 v[44:47], v80 offset:47616
	v_pk_fma_f32 v[8:9], v[4:5], v[14:15], v[8:9] op_sel_hi:[1,0,1]
	v_pk_fma_f32 v[10:11], v[4:5], v[18:19], v[10:11] op_sel_hi:[1,0,1]
	ds_read_b128 v[48:51], v80 offset:47872
	v_pk_fma_f32 v[8:9], v[6:7], v[14:15], v[8:9] op_sel:[0,1,0]
	v_pk_fma_f32 v[10:11], v[6:7], v[18:19], v[10:11] op_sel:[0,1,0]
	ds_read_b128 v[52:55], v80 offset:48128
	v_add_f32_dpp v74, v9, v8 row_ror:8 row_mask:0xf bank_mask:0xf bound_ctrl:1
	v_add_f32_dpp v75, v11, v10 row_ror:8 row_mask:0xf bank_mask:0xf bound_ctrl:1
	ds_read_b128 v[56:59], v80 offset:48640
	v_add_f32_dpp v74, v74, v74 quad_perm:[1,0,3,2] row_mask:0xf bank_mask:0xf bound_ctrl:1
	v_add_f32_dpp v75, v75, v75 quad_perm:[1,0,3,2] row_mask:0xf bank_mask:0xf bound_ctrl:1
	ds_read_b32 v60, v81 offset:48896
	v_add_f32_dpp v74, v74, v74 quad_perm:[2,3,0,1] row_mask:0xf bank_mask:0xf bound_ctrl:1
	v_add_f32_dpp v75, v75, v75 quad_perm:[2,3,0,1] row_mask:0xf bank_mask:0xf bound_ctrl:1
	ds_read_b32 v61, v82 offset:48896
	v_add_f32_dpp v76, v74, v74 row_half_mirror row_mask:0xf bank_mask:0xf bound_ctrl:1
	v_add_f32_dpp v36, v75, v75 row_half_mirror row_mask:0xf bank_mask:0xf bound_ctrl:1
	s_nop 0
	v_mov_b32_dpp v77, v76 row_ror:8 row_mask:0xf bank_mask:0xf bound_ctrl:1
	s_waitcnt lgkmcnt(9)
	v_pk_mul_f32 v[66:67], v[76:77], v[28:29] op_sel_hi:[1,0]
	v_pk_mul_f32 v[68:69], v[76:77], v[28:29] op_sel:[0,1]
	v_pk_mul_f32 v[70:71], v[76:77], v[30:31] op_sel_hi:[1,0]
	v_pk_mul_f32 v[72:73], v[76:77], v[30:31] op_sel:[0,1]
	v_pk_fma_f32 v[66:67], v[32:33], v[24:25], v[66:67] op_sel_hi:[1,0,1]
	v_pk_fma_f32 v[68:69], v[32:33], v[24:25], v[68:69] op_sel:[0,1,0]
	v_pk_fma_f32 v[70:71], v[32:33], v[26:27], v[70:71] op_sel_hi:[1,0,1]
	v_pk_fma_f32 v[72:73], v[32:33], v[26:27], v[72:73] op_sel:[0,1,0]
	v_pk_fma_f32 v[0:1], v[0:1], v[20:21], v[66:67] op_sel_hi:[1,0,1]
	v_pk_fma_f32 v[2:3], v[2:3], v[20:21], v[68:69] op_sel:[0,1,0]
	v_pk_fma_f32 v[4:5], v[4:5], v[22:23], v[70:71] op_sel_hi:[1,0,1]
	v_pk_fma_f32 v[6:7], v[6:7], v[22:23], v[72:73] op_sel:[0,1,0]
	ds_write_b32 v84, v36 offset:3840
	ds_write_b32 v84, v76 offset:16128
	s_waitcnt lgkmcnt(7)
	v_pk_mul_f32 v[8:9], v[0:1], v[40:41] op_sel_hi:[1,0]
	v_pk_mul_f32 v[10:11], v[0:1], v[44:45] op_sel_hi:[1,0]
	v_pk_fma_f32 v[8:9], v[2:3], v[40:41], v[8:9] op_sel:[0,1,0]
	v_pk_fma_f32 v[10:11], v[2:3], v[44:45], v[10:11] op_sel:[0,1,0]
	v_pk_fma_f32 v[8:9], v[4:5], v[42:43], v[8:9] op_sel_hi:[1,0,1]
	v_pk_fma_f32 v[10:11], v[4:5], v[46:47], v[10:11] op_sel_hi:[1,0,1]
	v_pk_fma_f32 v[8:9], v[6:7], v[42:43], v[8:9] op_sel:[0,1,0]
	v_pk_fma_f32 v[10:11], v[6:7], v[46:47], v[10:11] op_sel:[0,1,0]
	s_nop 0
	v_add_f32_dpp v74, v9, v8 row_ror:8 row_mask:0xf bank_mask:0xf bound_ctrl:1
	v_add_f32_dpp v75, v11, v10 row_ror:8 row_mask:0xf bank_mask:0xf bound_ctrl:1
	s_nop 0
	v_add_f32_dpp v74, v74, v74 quad_perm:[1,0,3,2] row_mask:0xf bank_mask:0xf bound_ctrl:1
	v_add_f32_dpp v75, v75, v75 quad_perm:[1,0,3,2] row_mask:0xf bank_mask:0xf bound_ctrl:1
	s_nop 0
	v_add_f32_dpp v74, v74, v74 quad_perm:[2,3,0,1] row_mask:0xf bank_mask:0xf bound_ctrl:1
	v_add_f32_dpp v75, v75, v75 quad_perm:[2,3,0,1] row_mask:0xf bank_mask:0xf bound_ctrl:1
	s_nop 0
	v_add_f32_dpp v76, v74, v74 row_half_mirror row_mask:0xf bank_mask:0xf bound_ctrl:1
	v_add_f32_dpp v64, v75, v75 row_half_mirror row_mask:0xf bank_mask:0xf bound_ctrl:1
	s_nop 0
	v_mov_b32_dpp v77, v76 row_ror:8 row_mask:0xf bank_mask:0xf bound_ctrl:1
	s_waitcnt lgkmcnt(2)
	v_pk_mul_f32 v[66:67], v[76:77], v[56:57] op_sel_hi:[1,0]
	v_pk_mul_f32 v[68:69], v[76:77], v[56:57] op_sel:[0,1]
	v_pk_mul_f32 v[70:71], v[76:77], v[58:59] op_sel_hi:[1,0]
	v_pk_mul_f32 v[72:73], v[76:77], v[58:59] op_sel:[0,1]
	v_pk_fma_f32 v[66:67], v[60:61], v[52:53], v[66:67] op_sel_hi:[1,0,1]
	v_pk_fma_f32 v[68:69], v[60:61], v[52:53], v[68:69] op_sel:[0,1,0]
	v_pk_fma_f32 v[70:71], v[60:61], v[54:55], v[70:71] op_sel_hi:[1,0,1]
	v_pk_fma_f32 v[72:73], v[60:61], v[54:55], v[72:73] op_sel:[0,1,0]
	v_pk_fma_f32 v[0:1], v[0:1], v[48:49], v[66:67] op_sel_hi:[1,0,1]
	v_pk_fma_f32 v[2:3], v[2:3], v[48:49], v[68:69] op_sel:[0,1,0]
	v_pk_fma_f32 v[4:5], v[4:5], v[50:51], v[70:71] op_sel_hi:[1,0,1]
	v_pk_fma_f32 v[6:7], v[6:7], v[50:51], v[72:73] op_sel:[0,1,0]
	ds_write_b32 v84, v64 offset:3968
	ds_write_b32 v84, v76 offset:16256
